# EpiRes epilogue (out/down GEMMs): both column-half residual loads issued together per row with counted vmcnt waits, second half no longer waits on first half's store acks
# speedup vs baseline: 1.0043x; 1.0043x over previous
; __device__ __forceinline__ float swz16(float v) { return __builtin_bit_cast(float, __builtin_amdgcn_ds_swizzle(__builtin_bit_cast(int, v), 0x401F)); }
;     __device__ __forceinline__ void operator()(const f32x4 (&acc)[2][2][4][2], const Unit& u, int wr, int wc, int fr, int fq) const {
;     ...
;                 const int row = row0 + ai * 128 + m * 16; float sq = 0.f;
; #pragma unroll
;                 for (int bj = 0; bj < 2; ++bj) {
;                     const size_t off = (size_t)row * DM + col0 + bj * 128;
;                     const f32x4 r0 = *(const f32x4*)(res + off), r1 = *(const f32x4*)(res + off + 4);
;                     const f32x4 v0 = acc[ai][bj][m][0] + r0, v1 = acc[ai][bj][m][1] + r1;
;                     *(f32x4*)(out + off) = v0; *(f32x4*)(out + off + 4) = v1;
;                     u32x4 o; o.x = pack2(v0[0], v0[1]); o.y = pack2(v0[2], v0[3]); o.z = pack2(v1[0], v1[1]); o.w = pack2(v1[2], v1[3]);
;                     *(u32x4*)(hb + off) = o;
;                     sq += v0[0] * v0[0] + v0[1] * v0[1] + v0[2] * v0[2] + v0[3] * v0[3] + v1[0] * v1[0] + v1[1] * v1[1] + v1[2] * v1[2] + v1[3] * v1[3];
;                 }
;                 sq += swz16(sq); sq = sum32(sq);
;                 if (fq == 0) ss_out[(size_t)row * 32 + u.pn * 4 + wc] = sq;
.LBB0_538:
	s_or_b64 exec, exec, s[40:41]
	v_or_b32_e32 v112, 16, v146
	v_ashrrev_i32_e32 v113, 31, v112
	v_lshlrev_b64 v[114:115], 11, v[112:113]
	v_lshl_add_u64 v[122:123], v[114:115], 0, v[144:145]
	v_lshlrev_b64 v[124:125], 2, v[122:123]
	v_lshl_add_u64 v[126:127], s[16:17], 0, v[124:125]
	global_load_dwordx4 v[114:117], v[126:127], off
	global_load_dwordx4 v[118:121], v[126:127], off offset:16
	global_load_dwordx4 v[230:233], v[126:127], off offset:512
	global_load_dwordx4 v[234:237], v[126:127], off offset:528
	v_lshl_add_u64 v[122:123], v[122:123], 1, s[14:15]
	v_lshl_add_u64 v[124:125], s[22:23], 0, v[124:125]
	s_waitcnt vmcnt(3)
	v_pk_add_f32 v[110:111], v[110:111], v[116:117]
	v_pk_add_f32 v[108:109], v[108:109], v[114:115]
	s_waitcnt vmcnt(2)
	v_pk_add_f32 v[106:107], v[106:107], v[120:121]
	v_pk_add_f32 v[104:105], v[104:105], v[118:119]
	v_cvt_pk_bf16_f32 v114, v108, v109
	v_cvt_pk_bf16_f32 v115, v110, v111
	v_cvt_pk_bf16_f32 v116, v104, v105
	v_cvt_pk_bf16_f32 v117, v106, v107
	global_store_dwordx4 v[124:125], v[108:111], off
	global_store_dwordx4 v[124:125], v[104:107], off offset:16
	global_store_dwordx4 v[122:123], v[114:117], off
	v_mul_f32_e32 v109, v109, v109
	v_fmac_f32_e32 v109, v108, v108
	v_fmac_f32_e32 v109, v110, v110
	v_fmac_f32_e32 v109, v111, v111
	v_fmac_f32_e32 v109, v104, v104
	v_fmac_f32_e32 v109, v105, v105
	v_fmac_f32_e32 v109, v106, v106
	v_fmac_f32_e32 v109, v107, v107
	s_waitcnt vmcnt(4)
	v_pk_add_f32 v[102:103], v[102:103], v[232:233]
	v_pk_add_f32 v[100:101], v[100:101], v[230:231]
	s_waitcnt vmcnt(3)
	v_pk_add_f32 v[98:99], v[98:99], v[236:237]
	v_pk_add_f32 v[96:97], v[96:97], v[234:235]
	global_store_dwordx4 v[124:125], v[100:103], off offset:512
	global_store_dwordx4 v[124:125], v[96:99], off offset:528
	v_cvt_pk_bf16_f32 v104, v100, v101
	v_mul_f32_e32 v101, v101, v101
	v_fmac_f32_e32 v101, v100, v100
	v_fmac_f32_e32 v101, v102, v102
	v_fmac_f32_e32 v101, v103, v103
	v_fmac_f32_e32 v101, v96, v96
	v_fmac_f32_e32 v101, v97, v97
	v_fmac_f32_e32 v101, v98, v98
	v_fmac_f32_e32 v101, v99, v99
	v_add_f32_e32 v100, v109, v101
	ds_swizzle_b32 v101, v100 offset:swizzle(SWAP,16)
	v_cvt_pk_bf16_f32 v106, v96, v97
	v_cvt_pk_bf16_f32 v105, v102, v103
	v_cvt_pk_bf16_f32 v107, v98, v99
	global_store_dwordx4 v[122:123], v[104:107], off offset:256
	s_waitcnt lgkmcnt(0)
	v_add_f32_e32 v96, v100, v101
	v_mov_b32_e32 v97, v96
	s_nop 1
	v_permlane32_swap_b32_e32 v96, v97
	s_and_saveexec_b64 s[40:41], s[8:9]
	s_cbranch_execz .LBB0_540
	v_add_f32_e32 v98, v96, v97
	v_lshlrev_b64 v[96:97], 7, v[112:113]
	v_lshl_add_u64 v[96:97], s[18:19], 0, v[96:97]
	v_lshl_add_u64 v[96:97], s[38:39], 2, v[96:97]
	s_lshl_b32 s24, s55, 2
	v_lshl_add_u64 v[96:97], v[96:97], 0, s[24:25]
	global_store_dword v[96:97], v98, off
.LBB0_540:
	s_or_b64 exec, exec, s[40:41]
	v_or_b32_e32 v96, 32, v146
	v_ashrrev_i32_e32 v97, 31, v96
	v_lshlrev_b64 v[98:99], 11, v[96:97]
	v_lshl_add_u64 v[106:107], v[98:99], 0, v[144:145]
	v_lshlrev_b64 v[108:109], 2, v[106:107]
	v_lshl_add_u64 v[110:111], s[16:17], 0, v[108:109]
	global_load_dwordx4 v[98:101], v[110:111], off
	global_load_dwordx4 v[102:105], v[110:111], off offset:16
	global_load_dwordx4 v[230:233], v[110:111], off offset:512
	global_load_dwordx4 v[234:237], v[110:111], off offset:528
	v_lshl_add_u64 v[106:107], v[106:107], 1, s[14:15]
	v_lshl_add_u64 v[108:109], s[22:23], 0, v[108:109]
	s_waitcnt vmcnt(3)
	v_pk_add_f32 v[94:95], v[94:95], v[100:101]
	v_pk_add_f32 v[92:93], v[92:93], v[98:99]
	s_waitcnt vmcnt(2)
	v_pk_add_f32 v[90:91], v[90:91], v[104:105]
	v_pk_add_f32 v[88:89], v[88:89], v[102:103]
	v_cvt_pk_bf16_f32 v98, v92, v93
	v_cvt_pk_bf16_f32 v99, v94, v95
	v_cvt_pk_bf16_f32 v100, v88, v89
	v_cvt_pk_bf16_f32 v101, v90, v91
	global_store_dwordx4 v[108:109], v[92:95], off
	global_store_dwordx4 v[108:109], v[88:91], off offset:16
	global_store_dwordx4 v[106:107], v[98:101], off
	v_mul_f32_e32 v93, v93, v93
	v_fmac_f32_e32 v93, v92, v92
	v_fmac_f32_e32 v93, v94, v94
	v_fmac_f32_e32 v93, v95, v95
	v_fmac_f32_e32 v93, v88, v88
	v_fmac_f32_e32 v93, v89, v89
	v_fmac_f32_e32 v93, v90, v90
	v_fmac_f32_e32 v93, v91, v91
	s_waitcnt vmcnt(4)
	v_pk_add_f32 v[86:87], v[86:87], v[232:233]
	v_pk_add_f32 v[84:85], v[84:85], v[230:231]
	s_waitcnt vmcnt(3)
	v_pk_add_f32 v[82:83], v[82:83], v[236:237]
	v_pk_add_f32 v[80:81], v[80:81], v[234:235]
	global_store_dwordx4 v[108:109], v[84:87], off offset:512
	global_store_dwordx4 v[108:109], v[80:83], off offset:528
	v_cvt_pk_bf16_f32 v88, v84, v85
	v_mul_f32_e32 v85, v85, v85
	v_fmac_f32_e32 v85, v84, v84
	v_fmac_f32_e32 v85, v86, v86
	v_fmac_f32_e32 v85, v87, v87
	v_fmac_f32_e32 v85, v80, v80
	v_fmac_f32_e32 v85, v81, v81
	v_fmac_f32_e32 v85, v82, v82
	v_fmac_f32_e32 v85, v83, v83
	v_add_f32_e32 v84, v93, v85
	ds_swizzle_b32 v85, v84 offset:swizzle(SWAP,16)
	v_cvt_pk_bf16_f32 v90, v80, v81
	v_cvt_pk_bf16_f32 v89, v86, v87
	v_cvt_pk_bf16_f32 v91, v82, v83
	global_store_dwordx4 v[106:107], v[88:91], off offset:256
	s_waitcnt lgkmcnt(0)
	v_add_f32_e32 v80, v84, v85
	v_mov_b32_e32 v81, v80
	s_nop 1
	v_permlane32_swap_b32_e32 v80, v81
	s_and_saveexec_b64 s[40:41], s[8:9]
	s_cbranch_execz .LBB0_542
	v_add_f32_e32 v82, v80, v81
	v_lshlrev_b64 v[80:81], 7, v[96:97]
	v_lshl_add_u64 v[80:81], s[18:19], 0, v[80:81]
	v_lshl_add_u64 v[80:81], s[38:39], 2, v[80:81]
	s_lshl_b32 s24, s55, 2
	v_lshl_add_u64 v[80:81], v[80:81], 0, s[24:25]
	global_store_dword v[80:81], v82, off
; __device__ __forceinline__ float swz16(float v) { return __builtin_bit_cast(float, __builtin_amdgcn_ds_swizzle(__builtin_bit_cast(int, v), 0x401F)); }
;     __device__ __forceinline__ void operator()(const f32x4 (&acc)[2][2][4][2], const Unit& u, int wr, int wc, int fr, int fq) const {
;     ...
;                 const int row = row0 + ai * 128 + m * 16; float sq = 0.f;
; #pragma unroll
;                 for (int bj = 0; bj < 2; ++bj) {
;                     const size_t off = (size_t)row * DM + col0 + bj * 128;
;                     const f32x4 r0 = *(const f32x4*)(res + off), r1 = *(const f32x4*)(res + off + 4);
;                     const f32x4 v0 = acc[ai][bj][m][0] + r0, v1 = acc[ai][bj][m][1] + r1;
;                     *(f32x4*)(out + off) = v0; *(f32x4*)(out + off + 4) = v1;
;                     u32x4 o; o.x = pack2(v0[0], v0[1]); o.y = pack2(v0[2], v0[3]); o.z = pack2(v1[0], v1[1]); o.w = pack2(v1[2], v1[3]);
;                     *(u32x4*)(hb + off) = o;
;                     sq += v0[0] * v0[0] + v0[1] * v0[1] + v0[2] * v0[2] + v0[3] * v0[3] + v1[0] * v1[0] + v1[1] * v1[1] + v1[2] * v1[2] + v1[3] * v1[3];
;                 }
;                 sq += swz16(sq); sq = sum32(sq);
;                 if (fq == 0) ss_out[(size_t)row * 32 + u.pn * 4 + wc] = sq;
.LBB0_542:
	s_or_b64 exec, exec, s[40:41]
	v_or_b32_e32 v80, 48, v146
	v_ashrrev_i32_e32 v81, 31, v80
	v_lshlrev_b64 v[82:83], 11, v[80:81]
	v_lshl_add_u64 v[90:91], v[82:83], 0, v[144:145]
	v_lshlrev_b64 v[92:93], 2, v[90:91]
	v_lshl_add_u64 v[94:95], s[16:17], 0, v[92:93]
	global_load_dwordx4 v[82:85], v[94:95], off
	global_load_dwordx4 v[86:89], v[94:95], off offset:16
	global_load_dwordx4 v[230:233], v[94:95], off offset:512
	global_load_dwordx4 v[234:237], v[94:95], off offset:528
	v_lshl_add_u64 v[90:91], v[90:91], 1, s[14:15]
	v_lshl_add_u64 v[92:93], s[22:23], 0, v[92:93]
	s_waitcnt vmcnt(3)
	v_pk_add_f32 v[78:79], v[78:79], v[84:85]
	v_pk_add_f32 v[76:77], v[76:77], v[82:83]
	s_waitcnt vmcnt(2)
	v_pk_add_f32 v[74:75], v[74:75], v[88:89]
	v_pk_add_f32 v[72:73], v[72:73], v[86:87]
	v_cvt_pk_bf16_f32 v82, v76, v77
	v_cvt_pk_bf16_f32 v83, v78, v79
	v_cvt_pk_bf16_f32 v84, v72, v73
	v_cvt_pk_bf16_f32 v85, v74, v75
	global_store_dwordx4 v[92:93], v[76:79], off
	global_store_dwordx4 v[92:93], v[72:75], off offset:16
	global_store_dwordx4 v[90:91], v[82:85], off
	v_mul_f32_e32 v77, v77, v77
	v_fmac_f32_e32 v77, v76, v76
	v_fmac_f32_e32 v77, v78, v78
	v_fmac_f32_e32 v77, v79, v79
	v_fmac_f32_e32 v77, v72, v72
	v_fmac_f32_e32 v77, v73, v73
	v_fmac_f32_e32 v77, v74, v74
	v_fmac_f32_e32 v77, v75, v75
	s_waitcnt vmcnt(4)
	v_pk_add_f32 v[70:71], v[70:71], v[232:233]
	v_pk_add_f32 v[68:69], v[68:69], v[230:231]
	s_waitcnt vmcnt(3)
	v_pk_add_f32 v[66:67], v[66:67], v[236:237]
	v_pk_add_f32 v[64:65], v[64:65], v[234:235]
	global_store_dwordx4 v[92:93], v[68:71], off offset:512
	global_store_dwordx4 v[92:93], v[64:67], off offset:528
	v_cvt_pk_bf16_f32 v72, v68, v69
	v_mul_f32_e32 v69, v69, v69
	v_fmac_f32_e32 v69, v68, v68
	v_fmac_f32_e32 v69, v70, v70
	v_fmac_f32_e32 v69, v71, v71
	v_fmac_f32_e32 v69, v64, v64
	v_fmac_f32_e32 v69, v65, v65
	v_fmac_f32_e32 v69, v66, v66
	v_fmac_f32_e32 v69, v67, v67
	v_add_f32_e32 v68, v77, v69
	ds_swizzle_b32 v69, v68 offset:swizzle(SWAP,16)
	v_cvt_pk_bf16_f32 v74, v64, v65
	v_cvt_pk_bf16_f32 v73, v70, v71
	v_cvt_pk_bf16_f32 v75, v66, v67
	global_store_dwordx4 v[90:91], v[72:75], off offset:256
	s_waitcnt lgkmcnt(0)
	v_add_f32_e32 v64, v68, v69
	v_mov_b32_e32 v65, v64
	s_nop 1
	v_permlane32_swap_b32_e32 v64, v65
	s_and_saveexec_b64 s[40:41], s[8:9]
	s_cbranch_execz .LBB0_544
	v_add_f32_e32 v66, v64, v65
	v_lshlrev_b64 v[64:65], 7, v[80:81]
	v_lshl_add_u64 v[64:65], s[18:19], 0, v[64:65]
	v_lshl_add_u64 v[64:65], s[38:39], 2, v[64:65]
	s_lshl_b32 s24, s55, 2
	v_lshl_add_u64 v[64:65], v[64:65], 0, s[24:25]
	global_store_dword v[64:65], v66, off
.LBB0_544:
	s_or_b64 exec, exec, s[40:41]
	v_add_u32_e32 v64, 0x80, v146
	v_ashrrev_i32_e32 v65, 31, v64
	v_lshlrev_b64 v[66:67], 11, v[64:65]
	v_lshl_add_u64 v[74:75], v[66:67], 0, v[144:145]
	v_lshlrev_b64 v[76:77], 2, v[74:75]
	v_lshl_add_u64 v[78:79], s[16:17], 0, v[76:77]
	global_load_dwordx4 v[66:69], v[78:79], off
	global_load_dwordx4 v[70:73], v[78:79], off offset:16
	global_load_dwordx4 v[230:233], v[78:79], off offset:512
	global_load_dwordx4 v[234:237], v[78:79], off offset:528
	v_lshl_add_u64 v[74:75], v[74:75], 1, s[14:15]
	v_lshl_add_u64 v[76:77], s[22:23], 0, v[76:77]
	s_waitcnt vmcnt(3)
	v_pk_add_f32 v[62:63], v[62:63], v[68:69]
	v_pk_add_f32 v[60:61], v[60:61], v[66:67]
	s_waitcnt vmcnt(2)
	v_pk_add_f32 v[58:59], v[58:59], v[72:73]
	v_pk_add_f32 v[56:57], v[56:57], v[70:71]
	v_cvt_pk_bf16_f32 v66, v60, v61
	v_cvt_pk_bf16_f32 v67, v62, v63
	v_cvt_pk_bf16_f32 v68, v56, v57
	v_cvt_pk_bf16_f32 v69, v58, v59
	global_store_dwordx4 v[76:77], v[60:63], off
	global_store_dwordx4 v[76:77], v[56:59], off offset:16
	global_store_dwordx4 v[74:75], v[66:69], off
	v_mul_f32_e32 v61, v61, v61
	v_fmac_f32_e32 v61, v60, v60
	v_fmac_f32_e32 v61, v62, v62
	v_fmac_f32_e32 v61, v63, v63
	v_fmac_f32_e32 v61, v56, v56
	v_fmac_f32_e32 v61, v57, v57
	v_fmac_f32_e32 v61, v58, v58
	v_fmac_f32_e32 v61, v59, v59
	s_waitcnt vmcnt(4)
	v_pk_add_f32 v[54:55], v[54:55], v[232:233]
	v_pk_add_f32 v[52:53], v[52:53], v[230:231]
	s_waitcnt vmcnt(3)
	v_pk_add_f32 v[50:51], v[50:51], v[236:237]
	v_pk_add_f32 v[48:49], v[48:49], v[234:235]
	global_store_dwordx4 v[76:77], v[52:55], off offset:512
	global_store_dwordx4 v[76:77], v[48:51], off offset:528
	v_cvt_pk_bf16_f32 v56, v52, v53
	v_mul_f32_e32 v53, v53, v53
	v_fmac_f32_e32 v53, v52, v52
	v_fmac_f32_e32 v53, v54, v54
	v_fmac_f32_e32 v53, v55, v55
	v_fmac_f32_e32 v53, v48, v48
	v_fmac_f32_e32 v53, v49, v49
	v_fmac_f32_e32 v53, v50, v50
	v_fmac_f32_e32 v53, v51, v51
	v_add_f32_e32 v52, v61, v53
	ds_swizzle_b32 v53, v52 offset:swizzle(SWAP,16)
	v_cvt_pk_bf16_f32 v58, v48, v49
	v_cvt_pk_bf16_f32 v57, v54, v55
	v_cvt_pk_bf16_f32 v59, v50, v51
	global_store_dwordx4 v[74:75], v[56:59], off offset:256
	s_waitcnt lgkmcnt(0)
	v_add_f32_e32 v48, v52, v53
	v_mov_b32_e32 v49, v48
	s_nop 1
	v_permlane32_swap_b32_e32 v48, v49
	s_and_saveexec_b64 s[40:41], s[8:9]
	s_cbranch_execz .LBB0_546
	v_add_f32_e32 v50, v48, v49
	v_lshlrev_b64 v[48:49], 7, v[64:65]
	v_lshl_add_u64 v[48:49], s[18:19], 0, v[48:49]
	v_lshl_add_u64 v[48:49], s[38:39], 2, v[48:49]
	s_lshl_b32 s24, s55, 2
	v_lshl_add_u64 v[48:49], v[48:49], 0, s[24:25]
	global_store_dword v[48:49], v50, off
; __device__ __forceinline__ float swz16(float v) { return __builtin_bit_cast(float, __builtin_amdgcn_ds_swizzle(__builtin_bit_cast(int, v), 0x401F)); }
;     __device__ __forceinline__ void operator()(const f32x4 (&acc)[2][2][4][2], const Unit& u, int wr, int wc, int fr, int fq) const {
;     ...
;                 const int row = row0 + ai * 128 + m * 16; float sq = 0.f;
; #pragma unroll
;                 for (int bj = 0; bj < 2; ++bj) {
;                     const size_t off = (size_t)row * DM + col0 + bj * 128;
;                     const f32x4 r0 = *(const f32x4*)(res + off), r1 = *(const f32x4*)(res + off + 4);
;                     const f32x4 v0 = acc[ai][bj][m][0] + r0, v1 = acc[ai][bj][m][1] + r1;
;                     *(f32x4*)(out + off) = v0; *(f32x4*)(out + off + 4) = v1;
;                     u32x4 o; o.x = pack2(v0[0], v0[1]); o.y = pack2(v0[2], v0[3]); o.z = pack2(v1[0], v1[1]); o.w = pack2(v1[2], v1[3]);
;                     *(u32x4*)(hb + off) = o;
;                     sq += v0[0] * v0[0] + v0[1] * v0[1] + v0[2] * v0[2] + v0[3] * v0[3] + v1[0] * v1[0] + v1[1] * v1[1] + v1[2] * v1[2] + v1[3] * v1[3];
;                 }
;                 sq += swz16(sq); sq = sum32(sq);
;                 if (fq == 0) ss_out[(size_t)row * 32 + u.pn * 4 + wc] = sq;
.LBB0_546:
	s_or_b64 exec, exec, s[40:41]
	v_add_u32_e32 v48, 0x90, v146
	v_ashrrev_i32_e32 v49, 31, v48
	v_lshlrev_b64 v[50:51], 11, v[48:49]
	v_lshl_add_u64 v[58:59], v[50:51], 0, v[144:145]
	v_lshlrev_b64 v[60:61], 2, v[58:59]
	v_lshl_add_u64 v[62:63], s[16:17], 0, v[60:61]
	global_load_dwordx4 v[50:53], v[62:63], off
	global_load_dwordx4 v[54:57], v[62:63], off offset:16
	global_load_dwordx4 v[230:233], v[62:63], off offset:512
	global_load_dwordx4 v[234:237], v[62:63], off offset:528
	v_lshl_add_u64 v[58:59], v[58:59], 1, s[14:15]
	v_lshl_add_u64 v[60:61], s[22:23], 0, v[60:61]
	s_waitcnt vmcnt(3)
	v_pk_add_f32 v[46:47], v[46:47], v[52:53]
	v_pk_add_f32 v[44:45], v[44:45], v[50:51]
	s_waitcnt vmcnt(2)
	v_pk_add_f32 v[42:43], v[42:43], v[56:57]
	v_pk_add_f32 v[40:41], v[40:41], v[54:55]
	v_cvt_pk_bf16_f32 v50, v44, v45
	v_cvt_pk_bf16_f32 v51, v46, v47
	v_cvt_pk_bf16_f32 v52, v40, v41
	v_cvt_pk_bf16_f32 v53, v42, v43
	global_store_dwordx4 v[60:61], v[44:47], off
	global_store_dwordx4 v[60:61], v[40:43], off offset:16
	global_store_dwordx4 v[58:59], v[50:53], off
	v_mul_f32_e32 v45, v45, v45
	v_fmac_f32_e32 v45, v44, v44
	v_fmac_f32_e32 v45, v46, v46
	v_fmac_f32_e32 v45, v47, v47
	v_fmac_f32_e32 v45, v40, v40
	v_fmac_f32_e32 v45, v41, v41
	v_fmac_f32_e32 v45, v42, v42
	v_fmac_f32_e32 v45, v43, v43
	s_waitcnt vmcnt(4)
	v_pk_add_f32 v[38:39], v[38:39], v[232:233]
	v_pk_add_f32 v[36:37], v[36:37], v[230:231]
	s_waitcnt vmcnt(3)
	v_pk_add_f32 v[34:35], v[34:35], v[236:237]
	v_pk_add_f32 v[32:33], v[32:33], v[234:235]
	global_store_dwordx4 v[60:61], v[36:39], off offset:512
	global_store_dwordx4 v[60:61], v[32:35], off offset:528
	v_cvt_pk_bf16_f32 v40, v36, v37
	v_mul_f32_e32 v37, v37, v37
	v_fmac_f32_e32 v37, v36, v36
	v_fmac_f32_e32 v37, v38, v38
	v_fmac_f32_e32 v37, v39, v39
	v_fmac_f32_e32 v37, v32, v32
	v_fmac_f32_e32 v37, v33, v33
	v_fmac_f32_e32 v37, v34, v34
	v_fmac_f32_e32 v37, v35, v35
	v_add_f32_e32 v36, v45, v37
	ds_swizzle_b32 v37, v36 offset:swizzle(SWAP,16)
	v_cvt_pk_bf16_f32 v42, v32, v33
	v_cvt_pk_bf16_f32 v41, v38, v39
	v_cvt_pk_bf16_f32 v43, v34, v35
	global_store_dwordx4 v[58:59], v[40:43], off offset:256
	s_waitcnt lgkmcnt(0)
	v_add_f32_e32 v32, v36, v37
	v_mov_b32_e32 v33, v32
	s_nop 1
	v_permlane32_swap_b32_e32 v32, v33
	s_and_saveexec_b64 s[40:41], s[8:9]
	s_cbranch_execz .LBB0_548
	v_add_f32_e32 v34, v32, v33
	v_lshlrev_b64 v[32:33], 7, v[48:49]
	v_lshl_add_u64 v[32:33], s[18:19], 0, v[32:33]
	v_lshl_add_u64 v[32:33], s[38:39], 2, v[32:33]
	s_lshl_b32 s24, s55, 2
	v_lshl_add_u64 v[32:33], v[32:33], 0, s[24:25]
	global_store_dword v[32:33], v34, off
; __device__ __forceinline__ float swz16(float v) { return __builtin_bit_cast(float, __builtin_amdgcn_ds_swizzle(__builtin_bit_cast(int, v), 0x401F)); }
;     __device__ __forceinline__ void operator()(const f32x4 (&acc)[2][2][4][2], const Unit& u, int wr, int wc, int fr, int fq) const {
;     ...
;                 const int row = row0 + ai * 128 + m * 16; float sq = 0.f;
; #pragma unroll
;                 for (int bj = 0; bj < 2; ++bj) {
;                     const size_t off = (size_t)row * DM + col0 + bj * 128;
;                     const f32x4 r0 = *(const f32x4*)(res + off), r1 = *(const f32x4*)(res + off + 4);
;                     const f32x4 v0 = acc[ai][bj][m][0] + r0, v1 = acc[ai][bj][m][1] + r1;
;                     *(f32x4*)(out + off) = v0; *(f32x4*)(out + off + 4) = v1;
;                     u32x4 o; o.x = pack2(v0[0], v0[1]); o.y = pack2(v0[2], v0[3]); o.z = pack2(v1[0], v1[1]); o.w = pack2(v1[2], v1[3]);
;                     *(u32x4*)(hb + off) = o;
;                     sq += v0[0] * v0[0] + v0[1] * v0[1] + v0[2] * v0[2] + v0[3] * v0[3] + v1[0] * v1[0] + v1[1] * v1[1] + v1[2] * v1[2] + v1[3] * v1[3];
;                 }
;                 sq += swz16(sq); sq = sum32(sq);
;                 if (fq == 0) ss_out[(size_t)row * 32 + u.pn * 4 + wc] = sq;
.LBB0_548:
	s_or_b64 exec, exec, s[40:41]
	v_add_u32_e32 v32, 0xa0, v146
	v_ashrrev_i32_e32 v33, 31, v32
	v_lshlrev_b64 v[34:35], 11, v[32:33]
	v_lshl_add_u64 v[42:43], v[34:35], 0, v[144:145]
	v_lshlrev_b64 v[44:45], 2, v[42:43]
	v_lshl_add_u64 v[46:47], s[16:17], 0, v[44:45]
	global_load_dwordx4 v[34:37], v[46:47], off
	global_load_dwordx4 v[38:41], v[46:47], off offset:16
	global_load_dwordx4 v[230:233], v[46:47], off offset:512
	global_load_dwordx4 v[234:237], v[46:47], off offset:528
	v_lshl_add_u64 v[42:43], v[42:43], 1, s[14:15]
	v_lshl_add_u64 v[44:45], s[22:23], 0, v[44:45]
	s_waitcnt vmcnt(3)
	v_pk_add_f32 v[30:31], v[30:31], v[36:37]
	v_pk_add_f32 v[28:29], v[28:29], v[34:35]
	s_waitcnt vmcnt(2)
	v_pk_add_f32 v[26:27], v[26:27], v[40:41]
	v_pk_add_f32 v[24:25], v[24:25], v[38:39]
	v_cvt_pk_bf16_f32 v34, v28, v29
	v_cvt_pk_bf16_f32 v35, v30, v31
	v_cvt_pk_bf16_f32 v36, v24, v25
	v_cvt_pk_bf16_f32 v37, v26, v27
	global_store_dwordx4 v[44:45], v[28:31], off
	global_store_dwordx4 v[44:45], v[24:27], off offset:16
	global_store_dwordx4 v[42:43], v[34:37], off
	v_mul_f32_e32 v29, v29, v29
	v_fmac_f32_e32 v29, v28, v28
	v_fmac_f32_e32 v29, v30, v30
	v_fmac_f32_e32 v29, v31, v31
	v_fmac_f32_e32 v29, v24, v24
	v_fmac_f32_e32 v29, v25, v25
	v_fmac_f32_e32 v29, v26, v26
	v_fmac_f32_e32 v29, v27, v27
	s_waitcnt vmcnt(4)
	v_pk_add_f32 v[22:23], v[22:23], v[232:233]
	v_pk_add_f32 v[20:21], v[20:21], v[230:231]
	s_waitcnt vmcnt(3)
	v_pk_add_f32 v[18:19], v[18:19], v[236:237]
	v_pk_add_f32 v[16:17], v[16:17], v[234:235]
	global_store_dwordx4 v[44:45], v[20:23], off offset:512
	global_store_dwordx4 v[44:45], v[16:19], off offset:528
	v_cvt_pk_bf16_f32 v24, v20, v21
	v_mul_f32_e32 v21, v21, v21
	v_fmac_f32_e32 v21, v20, v20
	v_fmac_f32_e32 v21, v22, v22
	v_fmac_f32_e32 v21, v23, v23
	v_fmac_f32_e32 v21, v16, v16
	v_fmac_f32_e32 v21, v17, v17
	v_fmac_f32_e32 v21, v18, v18
	v_fmac_f32_e32 v21, v19, v19
	v_add_f32_e32 v20, v29, v21
	ds_swizzle_b32 v21, v20 offset:swizzle(SWAP,16)
	v_cvt_pk_bf16_f32 v26, v16, v17
	v_cvt_pk_bf16_f32 v25, v22, v23
	v_cvt_pk_bf16_f32 v27, v18, v19
	global_store_dwordx4 v[42:43], v[24:27], off offset:256
	s_waitcnt lgkmcnt(0)
	v_add_f32_e32 v16, v20, v21
	v_mov_b32_e32 v17, v16
	s_nop 1
	v_permlane32_swap_b32_e32 v16, v17
	s_and_saveexec_b64 s[40:41], s[8:9]
	s_cbranch_execz .LBB0_550
	v_add_f32_e32 v18, v16, v17
	v_lshlrev_b64 v[16:17], 7, v[32:33]
	v_lshl_add_u64 v[16:17], s[18:19], 0, v[16:17]
	v_lshl_add_u64 v[16:17], s[38:39], 2, v[16:17]
	s_lshl_b32 s24, s55, 2
	v_lshl_add_u64 v[16:17], v[16:17], 0, s[24:25]
	global_store_dword v[16:17], v18, off
.LBB0_550:
	s_or_b64 exec, exec, s[40:41]
	v_add_u32_e32 v16, 0xb0, v146
	v_ashrrev_i32_e32 v17, 31, v16
	v_lshlrev_b64 v[18:19], 11, v[16:17]
	v_lshl_add_u64 v[26:27], v[18:19], 0, v[144:145]
	v_lshlrev_b64 v[28:29], 2, v[26:27]
	v_lshl_add_u64 v[30:31], s[16:17], 0, v[28:29]
	global_load_dwordx4 v[18:21], v[30:31], off
	global_load_dwordx4 v[22:25], v[30:31], off offset:16
	global_load_dwordx4 v[230:233], v[30:31], off offset:512
	global_load_dwordx4 v[234:237], v[30:31], off offset:528
	v_lshl_add_u64 v[26:27], v[26:27], 1, s[14:15]
	v_lshl_add_u64 v[28:29], s[22:23], 0, v[28:29]
	s_waitcnt vmcnt(3)
	v_pk_add_f32 v[14:15], v[14:15], v[20:21]
	v_pk_add_f32 v[12:13], v[12:13], v[18:19]
	s_waitcnt vmcnt(2)
	v_pk_add_f32 v[10:11], v[10:11], v[24:25]
	v_pk_add_f32 v[8:9], v[8:9], v[22:23]
	v_cvt_pk_bf16_f32 v18, v12, v13
	v_cvt_pk_bf16_f32 v19, v14, v15
	v_cvt_pk_bf16_f32 v20, v8, v9
	v_cvt_pk_bf16_f32 v21, v10, v11
	global_store_dwordx4 v[28:29], v[12:15], off
	global_store_dwordx4 v[28:29], v[8:11], off offset:16
	global_store_dwordx4 v[26:27], v[18:21], off
	v_mul_f32_e32 v13, v13, v13
	v_fmac_f32_e32 v13, v12, v12
	v_fmac_f32_e32 v13, v14, v14
	v_fmac_f32_e32 v13, v15, v15
	v_fmac_f32_e32 v13, v8, v8
	v_fmac_f32_e32 v13, v9, v9
	v_fmac_f32_e32 v13, v10, v10
	v_fmac_f32_e32 v13, v11, v11
	s_waitcnt vmcnt(4)
	v_pk_add_f32 v[6:7], v[6:7], v[232:233]
	v_pk_add_f32 v[4:5], v[4:5], v[230:231]
	s_waitcnt vmcnt(3)
	v_pk_add_f32 v[2:3], v[2:3], v[236:237]
	v_pk_add_f32 v[0:1], v[0:1], v[234:235]
	global_store_dwordx4 v[28:29], v[4:7], off offset:512
	global_store_dwordx4 v[28:29], v[0:3], off offset:528
	v_cvt_pk_bf16_f32 v8, v4, v5
	v_mul_f32_e32 v5, v5, v5
	v_fmac_f32_e32 v5, v4, v4
	v_fmac_f32_e32 v5, v6, v6
	v_fmac_f32_e32 v5, v7, v7
	v_fmac_f32_e32 v5, v0, v0
	v_fmac_f32_e32 v5, v1, v1
	v_fmac_f32_e32 v5, v2, v2
	v_fmac_f32_e32 v5, v3, v3
	v_add_f32_e32 v4, v13, v5
	ds_swizzle_b32 v5, v4 offset:swizzle(SWAP,16)
	v_cvt_pk_bf16_f32 v10, v0, v1
	v_cvt_pk_bf16_f32 v9, v6, v7
	v_cvt_pk_bf16_f32 v11, v2, v3
	global_store_dwordx4 v[26:27], v[8:11], off offset:256
	s_waitcnt lgkmcnt(0)
	v_add_f32_e32 v0, v4, v5
	v_mov_b32_e32 v1, v0
	s_nop 1
	v_permlane32_swap_b32_e32 v0, v1
	s_and_saveexec_b64 s[40:41], s[8:9]
	s_cbranch_execz .LBB0_527
	v_add_f32_e32 v2, v0, v1
	v_lshlrev_b64 v[0:1], 7, v[16:17]
	v_lshl_add_u64 v[0:1], s[18:19], 0, v[0:1]
	v_lshl_add_u64 v[0:1], s[38:39], 2, v[0:1]
	s_lshl_b32 s24, s55, 2
	v_lshl_add_u64 v[0:1], v[0:1], 0, s[24:25]
	global_store_dword v[0:1], v2, off
	s_branch .LBB0_527

; __device__ __forceinline__ float swz16(float v) { return __builtin_bit_cast(float, __builtin_amdgcn_ds_swizzle(__builtin_bit_cast(int, v), 0x401F)); }
;     __device__ __forceinline__ void operator()(const f32x4 (&acc)[2][2][4][2], const Unit& u, int wr, int wc, int fr, int fq) const {
;     ...
;                 const int row = row0 + ai * 128 + m * 16; float sq = 0.f;
; #pragma unroll
;                 for (int bj = 0; bj < 2; ++bj) {
;                     const size_t off = (size_t)row * DM + col0 + bj * 128;
;                     const f32x4 r0 = *(const f32x4*)(res + off), r1 = *(const f32x4*)(res + off + 4);
;                     const f32x4 v0 = acc[ai][bj][m][0] + r0, v1 = acc[ai][bj][m][1] + r1;
;                     *(f32x4*)(out + off) = v0; *(f32x4*)(out + off + 4) = v1;
;                     u32x4 o; o.x = pack2(v0[0], v0[1]); o.y = pack2(v0[2], v0[3]); o.z = pack2(v1[0], v1[1]); o.w = pack2(v1[2], v1[3]);
;                     *(u32x4*)(hb + off) = o;
;                     sq += v0[0] * v0[0] + v0[1] * v0[1] + v0[2] * v0[2] + v0[3] * v0[3] + v1[0] * v1[0] + v1[1] * v1[1] + v1[2] * v1[2] + v1[3] * v1[3];
;                 }
;                 sq += swz16(sq); sq = sum32(sq);
;                 if (fq == 0) ss_out[(size_t)row * 32 + u.pn * 4 + wc] = sq;
.LBB0_608:
	s_or_b64 exec, exec, s[38:39]
	v_or_b32_e32 v112, 16, v146
	v_ashrrev_i32_e32 v113, 31, v112
	v_lshlrev_b64 v[114:115], 11, v[112:113]
	v_lshl_add_u64 v[122:123], v[114:115], 0, v[144:145]
	v_lshl_add_u64 v[124:125], v[122:123], 2, s[12:13]
	global_load_dwordx4 v[114:117], v[124:125], off
	global_load_dwordx4 v[118:121], v[124:125], off offset:16
	global_load_dwordx4 v[230:233], v[124:125], off offset:512
	global_load_dwordx4 v[234:237], v[124:125], off offset:528
	v_lshl_add_u64 v[122:123], v[122:123], 1, s[16:17]
	s_waitcnt vmcnt(3)
	v_pk_add_f32 v[110:111], v[110:111], v[116:117]
	v_pk_add_f32 v[108:109], v[108:109], v[114:115]
	s_waitcnt vmcnt(2)
	v_pk_add_f32 v[106:107], v[106:107], v[120:121]
	v_pk_add_f32 v[104:105], v[104:105], v[118:119]
	v_cvt_pk_bf16_f32 v114, v108, v109
	v_cvt_pk_bf16_f32 v115, v110, v111
	v_cvt_pk_bf16_f32 v116, v104, v105
	v_cvt_pk_bf16_f32 v117, v106, v107
	global_store_dwordx4 v[124:125], v[108:111], off
	global_store_dwordx4 v[124:125], v[104:107], off offset:16
	global_store_dwordx4 v[122:123], v[114:117], off
	v_mul_f32_e32 v109, v109, v109
	v_fmac_f32_e32 v109, v108, v108
	v_fmac_f32_e32 v109, v110, v110
	v_fmac_f32_e32 v109, v111, v111
	v_fmac_f32_e32 v109, v104, v104
	v_fmac_f32_e32 v109, v105, v105
	v_fmac_f32_e32 v109, v106, v106
	v_fmac_f32_e32 v109, v107, v107
	s_waitcnt vmcnt(4)
	v_pk_add_f32 v[102:103], v[102:103], v[232:233]
	v_pk_add_f32 v[100:101], v[100:101], v[230:231]
	s_waitcnt vmcnt(3)
	v_pk_add_f32 v[98:99], v[98:99], v[236:237]
	v_pk_add_f32 v[96:97], v[96:97], v[234:235]
	global_store_dwordx4 v[124:125], v[100:103], off offset:512
	global_store_dwordx4 v[124:125], v[96:99], off offset:528
	v_cvt_pk_bf16_f32 v104, v100, v101
	v_mul_f32_e32 v101, v101, v101
	v_fmac_f32_e32 v101, v100, v100
	v_fmac_f32_e32 v101, v102, v102
	v_fmac_f32_e32 v101, v103, v103
	v_fmac_f32_e32 v101, v96, v96
	v_fmac_f32_e32 v101, v97, v97
	v_fmac_f32_e32 v101, v98, v98
	v_fmac_f32_e32 v101, v99, v99
	v_add_f32_e32 v100, v109, v101
	ds_swizzle_b32 v101, v100 offset:swizzle(SWAP,16)
	v_cvt_pk_bf16_f32 v106, v96, v97
	v_cvt_pk_bf16_f32 v105, v102, v103
	v_cvt_pk_bf16_f32 v107, v98, v99
	global_store_dwordx4 v[122:123], v[104:107], off offset:256
	s_waitcnt lgkmcnt(0)
	v_add_f32_e32 v96, v100, v101
	v_mov_b32_e32 v97, v96
	s_nop 1
	v_permlane32_swap_b32_e32 v96, v97
	s_and_saveexec_b64 s[38:39], s[8:9]
	s_cbranch_execz .LBB0_610
	v_add_f32_e32 v98, v96, v97
	v_lshlrev_b64 v[96:97], 7, v[112:113]
	v_lshl_add_u64 v[96:97], s[20:21], 0, v[96:97]
	v_lshl_add_u64 v[96:97], s[36:37], 2, v[96:97]
	s_lshl_b32 s22, s53, 2
	v_lshl_add_u64 v[96:97], v[96:97], 0, s[22:23]
	global_store_dword v[96:97], v98, off
.LBB0_610:
	s_or_b64 exec, exec, s[38:39]
	v_or_b32_e32 v96, 32, v146
	v_ashrrev_i32_e32 v97, 31, v96
	v_lshlrev_b64 v[98:99], 11, v[96:97]
	v_lshl_add_u64 v[106:107], v[98:99], 0, v[144:145]
	v_lshl_add_u64 v[108:109], v[106:107], 2, s[12:13]
	global_load_dwordx4 v[98:101], v[108:109], off
	global_load_dwordx4 v[102:105], v[108:109], off offset:16
	global_load_dwordx4 v[230:233], v[108:109], off offset:512
	global_load_dwordx4 v[234:237], v[108:109], off offset:528
	v_lshl_add_u64 v[106:107], v[106:107], 1, s[16:17]
	s_waitcnt vmcnt(3)
	v_pk_add_f32 v[94:95], v[94:95], v[100:101]
	v_pk_add_f32 v[92:93], v[92:93], v[98:99]
	s_waitcnt vmcnt(2)
	v_pk_add_f32 v[90:91], v[90:91], v[104:105]
	v_pk_add_f32 v[88:89], v[88:89], v[102:103]
	v_cvt_pk_bf16_f32 v98, v92, v93
	v_cvt_pk_bf16_f32 v99, v94, v95
	v_cvt_pk_bf16_f32 v100, v88, v89
	v_cvt_pk_bf16_f32 v101, v90, v91
	global_store_dwordx4 v[108:109], v[92:95], off
	global_store_dwordx4 v[108:109], v[88:91], off offset:16
	global_store_dwordx4 v[106:107], v[98:101], off
	v_mul_f32_e32 v93, v93, v93
	v_fmac_f32_e32 v93, v92, v92
	v_fmac_f32_e32 v93, v94, v94
	v_fmac_f32_e32 v93, v95, v95
	v_fmac_f32_e32 v93, v88, v88
	v_fmac_f32_e32 v93, v89, v89
	v_fmac_f32_e32 v93, v90, v90
	v_fmac_f32_e32 v93, v91, v91
	s_waitcnt vmcnt(4)
	v_pk_add_f32 v[86:87], v[86:87], v[232:233]
	v_pk_add_f32 v[84:85], v[84:85], v[230:231]
	s_waitcnt vmcnt(3)
	v_pk_add_f32 v[82:83], v[82:83], v[236:237]
	v_pk_add_f32 v[80:81], v[80:81], v[234:235]
	global_store_dwordx4 v[108:109], v[84:87], off offset:512
	global_store_dwordx4 v[108:109], v[80:83], off offset:528
	v_cvt_pk_bf16_f32 v88, v84, v85
	v_mul_f32_e32 v85, v85, v85
	v_fmac_f32_e32 v85, v84, v84
	v_fmac_f32_e32 v85, v86, v86
	v_fmac_f32_e32 v85, v87, v87
	v_fmac_f32_e32 v85, v80, v80
	v_fmac_f32_e32 v85, v81, v81
	v_fmac_f32_e32 v85, v82, v82
	v_fmac_f32_e32 v85, v83, v83
	v_add_f32_e32 v84, v93, v85
	ds_swizzle_b32 v85, v84 offset:swizzle(SWAP,16)
	v_cvt_pk_bf16_f32 v90, v80, v81
	v_cvt_pk_bf16_f32 v89, v86, v87
	v_cvt_pk_bf16_f32 v91, v82, v83
	global_store_dwordx4 v[106:107], v[88:91], off offset:256
	s_waitcnt lgkmcnt(0)
	v_add_f32_e32 v80, v84, v85
	v_mov_b32_e32 v81, v80
	s_nop 1
	v_permlane32_swap_b32_e32 v80, v81
	s_and_saveexec_b64 s[38:39], s[8:9]
	s_cbranch_execz .LBB0_612
	v_add_f32_e32 v82, v80, v81
	v_lshlrev_b64 v[80:81], 7, v[96:97]
	v_lshl_add_u64 v[80:81], s[20:21], 0, v[80:81]
	v_lshl_add_u64 v[80:81], s[36:37], 2, v[80:81]
	s_lshl_b32 s22, s53, 2
	v_lshl_add_u64 v[80:81], v[80:81], 0, s[22:23]
	global_store_dword v[80:81], v82, off
; __device__ __forceinline__ float swz16(float v) { return __builtin_bit_cast(float, __builtin_amdgcn_ds_swizzle(__builtin_bit_cast(int, v), 0x401F)); }
;     __device__ __forceinline__ void operator()(const f32x4 (&acc)[2][2][4][2], const Unit& u, int wr, int wc, int fr, int fq) const {
;     ...
;                 const int row = row0 + ai * 128 + m * 16; float sq = 0.f;
; #pragma unroll
;                 for (int bj = 0; bj < 2; ++bj) {
;                     const size_t off = (size_t)row * DM + col0 + bj * 128;
;                     const f32x4 r0 = *(const f32x4*)(res + off), r1 = *(const f32x4*)(res + off + 4);
;                     const f32x4 v0 = acc[ai][bj][m][0] + r0, v1 = acc[ai][bj][m][1] + r1;
;                     *(f32x4*)(out + off) = v0; *(f32x4*)(out + off + 4) = v1;
;                     u32x4 o; o.x = pack2(v0[0], v0[1]); o.y = pack2(v0[2], v0[3]); o.z = pack2(v1[0], v1[1]); o.w = pack2(v1[2], v1[3]);
;                     *(u32x4*)(hb + off) = o;
;                     sq += v0[0] * v0[0] + v0[1] * v0[1] + v0[2] * v0[2] + v0[3] * v0[3] + v1[0] * v1[0] + v1[1] * v1[1] + v1[2] * v1[2] + v1[3] * v1[3];
;                 }
;                 sq += swz16(sq); sq = sum32(sq);
;                 if (fq == 0) ss_out[(size_t)row * 32 + u.pn * 4 + wc] = sq;
.LBB0_612:
	s_or_b64 exec, exec, s[38:39]
	v_or_b32_e32 v80, 48, v146
	v_ashrrev_i32_e32 v81, 31, v80
	v_lshlrev_b64 v[82:83], 11, v[80:81]
	v_lshl_add_u64 v[90:91], v[82:83], 0, v[144:145]
	v_lshl_add_u64 v[92:93], v[90:91], 2, s[12:13]
	global_load_dwordx4 v[82:85], v[92:93], off
	global_load_dwordx4 v[86:89], v[92:93], off offset:16
	global_load_dwordx4 v[230:233], v[92:93], off offset:512
	global_load_dwordx4 v[234:237], v[92:93], off offset:528
	v_lshl_add_u64 v[90:91], v[90:91], 1, s[16:17]
	s_waitcnt vmcnt(3)
	v_pk_add_f32 v[78:79], v[78:79], v[84:85]
	v_pk_add_f32 v[76:77], v[76:77], v[82:83]
	s_waitcnt vmcnt(2)
	v_pk_add_f32 v[74:75], v[74:75], v[88:89]
	v_pk_add_f32 v[72:73], v[72:73], v[86:87]
	v_cvt_pk_bf16_f32 v82, v76, v77
	v_cvt_pk_bf16_f32 v83, v78, v79
	v_cvt_pk_bf16_f32 v84, v72, v73
	v_cvt_pk_bf16_f32 v85, v74, v75
	global_store_dwordx4 v[92:93], v[76:79], off
	global_store_dwordx4 v[92:93], v[72:75], off offset:16
	global_store_dwordx4 v[90:91], v[82:85], off
	v_mul_f32_e32 v77, v77, v77
	v_fmac_f32_e32 v77, v76, v76
	v_fmac_f32_e32 v77, v78, v78
	v_fmac_f32_e32 v77, v79, v79
	v_fmac_f32_e32 v77, v72, v72
	v_fmac_f32_e32 v77, v73, v73
	v_fmac_f32_e32 v77, v74, v74
	v_fmac_f32_e32 v77, v75, v75
	s_waitcnt vmcnt(4)
	v_pk_add_f32 v[70:71], v[70:71], v[232:233]
	v_pk_add_f32 v[68:69], v[68:69], v[230:231]
	s_waitcnt vmcnt(3)
	v_pk_add_f32 v[66:67], v[66:67], v[236:237]
	v_pk_add_f32 v[64:65], v[64:65], v[234:235]
	global_store_dwordx4 v[92:93], v[68:71], off offset:512
	global_store_dwordx4 v[92:93], v[64:67], off offset:528
	v_cvt_pk_bf16_f32 v72, v68, v69
	v_mul_f32_e32 v69, v69, v69
	v_fmac_f32_e32 v69, v68, v68
	v_fmac_f32_e32 v69, v70, v70
	v_fmac_f32_e32 v69, v71, v71
	v_fmac_f32_e32 v69, v64, v64
	v_fmac_f32_e32 v69, v65, v65
	v_fmac_f32_e32 v69, v66, v66
	v_fmac_f32_e32 v69, v67, v67
	v_add_f32_e32 v68, v77, v69
	ds_swizzle_b32 v69, v68 offset:swizzle(SWAP,16)
	v_cvt_pk_bf16_f32 v74, v64, v65
	v_cvt_pk_bf16_f32 v73, v70, v71
	v_cvt_pk_bf16_f32 v75, v66, v67
	global_store_dwordx4 v[90:91], v[72:75], off offset:256
	s_waitcnt lgkmcnt(0)
	v_add_f32_e32 v64, v68, v69
	v_mov_b32_e32 v65, v64
	s_nop 1
	v_permlane32_swap_b32_e32 v64, v65
	s_and_saveexec_b64 s[38:39], s[8:9]
	s_cbranch_execz .LBB0_614
	v_add_f32_e32 v66, v64, v65
	v_lshlrev_b64 v[64:65], 7, v[80:81]
	v_lshl_add_u64 v[64:65], s[20:21], 0, v[64:65]
	v_lshl_add_u64 v[64:65], s[36:37], 2, v[64:65]
	s_lshl_b32 s22, s53, 2
	v_lshl_add_u64 v[64:65], v[64:65], 0, s[22:23]
	global_store_dword v[64:65], v66, off
.LBB0_614:
	s_or_b64 exec, exec, s[38:39]
	v_add_u32_e32 v64, 0x80, v146
	v_ashrrev_i32_e32 v65, 31, v64
	v_lshlrev_b64 v[66:67], 11, v[64:65]
	v_lshl_add_u64 v[74:75], v[66:67], 0, v[144:145]
	v_lshl_add_u64 v[76:77], v[74:75], 2, s[12:13]
	global_load_dwordx4 v[66:69], v[76:77], off
	global_load_dwordx4 v[70:73], v[76:77], off offset:16
	global_load_dwordx4 v[230:233], v[76:77], off offset:512
	global_load_dwordx4 v[234:237], v[76:77], off offset:528
	v_lshl_add_u64 v[74:75], v[74:75], 1, s[16:17]
	s_waitcnt vmcnt(3)
	v_pk_add_f32 v[62:63], v[62:63], v[68:69]
	v_pk_add_f32 v[60:61], v[60:61], v[66:67]
	s_waitcnt vmcnt(2)
	v_pk_add_f32 v[58:59], v[58:59], v[72:73]
	v_pk_add_f32 v[56:57], v[56:57], v[70:71]
	v_cvt_pk_bf16_f32 v66, v60, v61
	v_cvt_pk_bf16_f32 v67, v62, v63
	v_cvt_pk_bf16_f32 v68, v56, v57
	v_cvt_pk_bf16_f32 v69, v58, v59
	global_store_dwordx4 v[76:77], v[60:63], off
	global_store_dwordx4 v[76:77], v[56:59], off offset:16
	global_store_dwordx4 v[74:75], v[66:69], off
	v_mul_f32_e32 v61, v61, v61
	v_fmac_f32_e32 v61, v60, v60
	v_fmac_f32_e32 v61, v62, v62
	v_fmac_f32_e32 v61, v63, v63
	v_fmac_f32_e32 v61, v56, v56
	v_fmac_f32_e32 v61, v57, v57
	v_fmac_f32_e32 v61, v58, v58
	v_fmac_f32_e32 v61, v59, v59
	s_waitcnt vmcnt(4)
	v_pk_add_f32 v[54:55], v[54:55], v[232:233]
	v_pk_add_f32 v[52:53], v[52:53], v[230:231]
	s_waitcnt vmcnt(3)
	v_pk_add_f32 v[50:51], v[50:51], v[236:237]
	v_pk_add_f32 v[48:49], v[48:49], v[234:235]
	global_store_dwordx4 v[76:77], v[52:55], off offset:512
	global_store_dwordx4 v[76:77], v[48:51], off offset:528
	v_cvt_pk_bf16_f32 v56, v52, v53
	v_mul_f32_e32 v53, v53, v53
	v_fmac_f32_e32 v53, v52, v52
	v_fmac_f32_e32 v53, v54, v54
	v_fmac_f32_e32 v53, v55, v55
	v_fmac_f32_e32 v53, v48, v48
	v_fmac_f32_e32 v53, v49, v49
	v_fmac_f32_e32 v53, v50, v50
	v_fmac_f32_e32 v53, v51, v51
	v_add_f32_e32 v52, v61, v53
	ds_swizzle_b32 v53, v52 offset:swizzle(SWAP,16)
	v_cvt_pk_bf16_f32 v58, v48, v49
	v_cvt_pk_bf16_f32 v57, v54, v55
	v_cvt_pk_bf16_f32 v59, v50, v51
	global_store_dwordx4 v[74:75], v[56:59], off offset:256
	s_waitcnt lgkmcnt(0)
	v_add_f32_e32 v48, v52, v53
	v_mov_b32_e32 v49, v48
	s_nop 1
	v_permlane32_swap_b32_e32 v48, v49
	s_and_saveexec_b64 s[38:39], s[8:9]
	s_cbranch_execz .LBB0_616
	v_add_f32_e32 v50, v48, v49
	v_lshlrev_b64 v[48:49], 7, v[64:65]
	v_lshl_add_u64 v[48:49], s[20:21], 0, v[48:49]
	v_lshl_add_u64 v[48:49], s[36:37], 2, v[48:49]
	s_lshl_b32 s22, s53, 2
	v_lshl_add_u64 v[48:49], v[48:49], 0, s[22:23]
	global_store_dword v[48:49], v50, off
; __device__ __forceinline__ float swz16(float v) { return __builtin_bit_cast(float, __builtin_amdgcn_ds_swizzle(__builtin_bit_cast(int, v), 0x401F)); }
;     __device__ __forceinline__ void operator()(const f32x4 (&acc)[2][2][4][2], const Unit& u, int wr, int wc, int fr, int fq) const {
;     ...
;                 const int row = row0 + ai * 128 + m * 16; float sq = 0.f;
; #pragma unroll
;                 for (int bj = 0; bj < 2; ++bj) {
;                     const size_t off = (size_t)row * DM + col0 + bj * 128;
;                     const f32x4 r0 = *(const f32x4*)(res + off), r1 = *(const f32x4*)(res + off + 4);
;                     const f32x4 v0 = acc[ai][bj][m][0] + r0, v1 = acc[ai][bj][m][1] + r1;
;                     *(f32x4*)(out + off) = v0; *(f32x4*)(out + off + 4) = v1;
;                     u32x4 o; o.x = pack2(v0[0], v0[1]); o.y = pack2(v0[2], v0[3]); o.z = pack2(v1[0], v1[1]); o.w = pack2(v1[2], v1[3]);
;                     *(u32x4*)(hb + off) = o;
;                     sq += v0[0] * v0[0] + v0[1] * v0[1] + v0[2] * v0[2] + v0[3] * v0[3] + v1[0] * v1[0] + v1[1] * v1[1] + v1[2] * v1[2] + v1[3] * v1[3];
;                 }
;                 sq += swz16(sq); sq = sum32(sq);
;                 if (fq == 0) ss_out[(size_t)row * 32 + u.pn * 4 + wc] = sq;
.LBB0_616:
	s_or_b64 exec, exec, s[38:39]
	v_add_u32_e32 v48, 0x90, v146
	v_ashrrev_i32_e32 v49, 31, v48
	v_lshlrev_b64 v[50:51], 11, v[48:49]
	v_lshl_add_u64 v[58:59], v[50:51], 0, v[144:145]
	v_lshl_add_u64 v[60:61], v[58:59], 2, s[12:13]
	global_load_dwordx4 v[50:53], v[60:61], off
	global_load_dwordx4 v[54:57], v[60:61], off offset:16
	global_load_dwordx4 v[230:233], v[60:61], off offset:512
	global_load_dwordx4 v[234:237], v[60:61], off offset:528
	v_lshl_add_u64 v[58:59], v[58:59], 1, s[16:17]
	s_waitcnt vmcnt(3)
	v_pk_add_f32 v[46:47], v[46:47], v[52:53]
	v_pk_add_f32 v[44:45], v[44:45], v[50:51]
	s_waitcnt vmcnt(2)
	v_pk_add_f32 v[42:43], v[42:43], v[56:57]
	v_pk_add_f32 v[40:41], v[40:41], v[54:55]
	v_cvt_pk_bf16_f32 v50, v44, v45
	v_cvt_pk_bf16_f32 v51, v46, v47
	v_cvt_pk_bf16_f32 v52, v40, v41
	v_cvt_pk_bf16_f32 v53, v42, v43
	global_store_dwordx4 v[60:61], v[44:47], off
	global_store_dwordx4 v[60:61], v[40:43], off offset:16
	global_store_dwordx4 v[58:59], v[50:53], off
	v_mul_f32_e32 v45, v45, v45
	v_fmac_f32_e32 v45, v44, v44
	v_fmac_f32_e32 v45, v46, v46
	v_fmac_f32_e32 v45, v47, v47
	v_fmac_f32_e32 v45, v40, v40
	v_fmac_f32_e32 v45, v41, v41
	v_fmac_f32_e32 v45, v42, v42
	v_fmac_f32_e32 v45, v43, v43
	s_waitcnt vmcnt(4)
	v_pk_add_f32 v[38:39], v[38:39], v[232:233]
	v_pk_add_f32 v[36:37], v[36:37], v[230:231]
	s_waitcnt vmcnt(3)
	v_pk_add_f32 v[34:35], v[34:35], v[236:237]
	v_pk_add_f32 v[32:33], v[32:33], v[234:235]
	global_store_dwordx4 v[60:61], v[36:39], off offset:512
	global_store_dwordx4 v[60:61], v[32:35], off offset:528
	v_cvt_pk_bf16_f32 v40, v36, v37
	v_mul_f32_e32 v37, v37, v37
	v_fmac_f32_e32 v37, v36, v36
	v_fmac_f32_e32 v37, v38, v38
	v_fmac_f32_e32 v37, v39, v39
	v_fmac_f32_e32 v37, v32, v32
	v_fmac_f32_e32 v37, v33, v33
	v_fmac_f32_e32 v37, v34, v34
	v_fmac_f32_e32 v37, v35, v35
	v_add_f32_e32 v36, v45, v37
	ds_swizzle_b32 v37, v36 offset:swizzle(SWAP,16)
	v_cvt_pk_bf16_f32 v42, v32, v33
	v_cvt_pk_bf16_f32 v41, v38, v39
	v_cvt_pk_bf16_f32 v43, v34, v35
	global_store_dwordx4 v[58:59], v[40:43], off offset:256
	s_waitcnt lgkmcnt(0)
	v_add_f32_e32 v32, v36, v37
	v_mov_b32_e32 v33, v32
	s_nop 1
	v_permlane32_swap_b32_e32 v32, v33
	s_and_saveexec_b64 s[38:39], s[8:9]
	s_cbranch_execz .LBB0_618
	v_add_f32_e32 v34, v32, v33
	v_lshlrev_b64 v[32:33], 7, v[48:49]
	v_lshl_add_u64 v[32:33], s[20:21], 0, v[32:33]
	v_lshl_add_u64 v[32:33], s[36:37], 2, v[32:33]
	s_lshl_b32 s22, s53, 2
	v_lshl_add_u64 v[32:33], v[32:33], 0, s[22:23]
	global_store_dword v[32:33], v34, off
; __device__ __forceinline__ float swz16(float v) { return __builtin_bit_cast(float, __builtin_amdgcn_ds_swizzle(__builtin_bit_cast(int, v), 0x401F)); }
;     __device__ __forceinline__ void operator()(const f32x4 (&acc)[2][2][4][2], const Unit& u, int wr, int wc, int fr, int fq) const {
;     ...
;         for (int ai = 0; ai < 2; ++ai)
; #pragma unroll
;             for (int m = 0; m < 4; ++m) {
;                 const int row = row0 + ai * 128 + m * 16; float sq = 0.f;
; #pragma unroll
;                 for (int bj = 0; bj < 2; ++bj) {
;                     const size_t off = (size_t)row * DM + col0 + bj * 128;
;                     const f32x4 r0 = *(const f32x4*)(res + off), r1 = *(const f32x4*)(res + off + 4);
;                     const f32x4 v0 = acc[ai][bj][m][0] + r0, v1 = acc[ai][bj][m][1] + r1;
;                     *(f32x4*)(out + off) = v0; *(f32x4*)(out + off + 4) = v1;
;                     u32x4 o; o.x = pack2(v0[0], v0[1]); o.y = pack2(v0[2], v0[3]); o.z = pack2(v1[0], v1[1]); o.w = pack2(v1[2], v1[3]);
;                     *(u32x4*)(hb + off) = o;
;                     sq += v0[0] * v0[0] + v0[1] * v0[1] + v0[2] * v0[2] + v0[3] * v0[3] + v1[0] * v1[0] + v1[1] * v1[1] + v1[2] * v1[2] + v1[3] * v1[3];
;                 }
;                 sq += swz16(sq); sq = sum32(sq);
;                 if (fq == 0) ss_out[(size_t)row * 32 + u.pn * 4 + wc] = sq;
;             }
.LBB0_618:
	s_or_b64 exec, exec, s[38:39]
	v_add_u32_e32 v32, 0xa0, v146
	v_ashrrev_i32_e32 v33, 31, v32
	v_lshlrev_b64 v[34:35], 11, v[32:33]
	v_lshl_add_u64 v[42:43], v[34:35], 0, v[144:145]
	v_lshl_add_u64 v[44:45], v[42:43], 2, s[12:13]
	global_load_dwordx4 v[34:37], v[44:45], off
	global_load_dwordx4 v[38:41], v[44:45], off offset:16
	global_load_dwordx4 v[230:233], v[44:45], off offset:512
	global_load_dwordx4 v[234:237], v[44:45], off offset:528
	v_lshl_add_u64 v[42:43], v[42:43], 1, s[16:17]
	s_waitcnt vmcnt(3)
	v_pk_add_f32 v[30:31], v[30:31], v[36:37]
	v_pk_add_f32 v[28:29], v[28:29], v[34:35]
	s_waitcnt vmcnt(2)
	v_pk_add_f32 v[26:27], v[26:27], v[40:41]
	v_pk_add_f32 v[24:25], v[24:25], v[38:39]
	v_cvt_pk_bf16_f32 v34, v28, v29
	v_cvt_pk_bf16_f32 v35, v30, v31
	v_cvt_pk_bf16_f32 v36, v24, v25
	v_cvt_pk_bf16_f32 v37, v26, v27
	global_store_dwordx4 v[44:45], v[28:31], off
	global_store_dwordx4 v[44:45], v[24:27], off offset:16
	global_store_dwordx4 v[42:43], v[34:37], off
	v_mul_f32_e32 v29, v29, v29
	v_fmac_f32_e32 v29, v28, v28
	v_fmac_f32_e32 v29, v30, v30
	v_fmac_f32_e32 v29, v31, v31
	v_fmac_f32_e32 v29, v24, v24
	v_fmac_f32_e32 v29, v25, v25
	v_fmac_f32_e32 v29, v26, v26
	v_fmac_f32_e32 v29, v27, v27
	s_waitcnt vmcnt(4)
	v_pk_add_f32 v[22:23], v[22:23], v[232:233]
	v_pk_add_f32 v[20:21], v[20:21], v[230:231]
	s_waitcnt vmcnt(3)
	v_pk_add_f32 v[18:19], v[18:19], v[236:237]
	v_pk_add_f32 v[16:17], v[16:17], v[234:235]
	global_store_dwordx4 v[44:45], v[20:23], off offset:512
	global_store_dwordx4 v[44:45], v[16:19], off offset:528
	v_cvt_pk_bf16_f32 v24, v20, v21
	v_mul_f32_e32 v21, v21, v21
	v_fmac_f32_e32 v21, v20, v20
	v_fmac_f32_e32 v21, v22, v22
	v_fmac_f32_e32 v21, v23, v23
	v_fmac_f32_e32 v21, v16, v16
	v_fmac_f32_e32 v21, v17, v17
	v_fmac_f32_e32 v21, v18, v18
	v_fmac_f32_e32 v21, v19, v19
	v_add_f32_e32 v20, v29, v21
	ds_swizzle_b32 v21, v20 offset:swizzle(SWAP,16)
	v_cvt_pk_bf16_f32 v26, v16, v17
	v_cvt_pk_bf16_f32 v25, v22, v23
	v_cvt_pk_bf16_f32 v27, v18, v19
	global_store_dwordx4 v[42:43], v[24:27], off offset:256
	s_waitcnt lgkmcnt(0)
	v_add_f32_e32 v16, v20, v21
	v_mov_b32_e32 v17, v16
	s_nop 1
	v_permlane32_swap_b32_e32 v16, v17
	s_and_saveexec_b64 s[38:39], s[8:9]
	s_cbranch_execz .LBB0_620
	v_add_f32_e32 v18, v16, v17
	v_lshlrev_b64 v[16:17], 7, v[32:33]
	v_lshl_add_u64 v[16:17], s[20:21], 0, v[16:17]
	v_lshl_add_u64 v[16:17], s[36:37], 2, v[16:17]
	s_lshl_b32 s22, s53, 2
	v_lshl_add_u64 v[16:17], v[16:17], 0, s[22:23]
	global_store_dword v[16:17], v18, off
.LBB0_620:
	s_or_b64 exec, exec, s[38:39]
	v_add_u32_e32 v16, 0xb0, v146
	v_ashrrev_i32_e32 v17, 31, v16
	v_lshlrev_b64 v[18:19], 11, v[16:17]
	v_lshl_add_u64 v[26:27], v[18:19], 0, v[144:145]
	v_lshl_add_u64 v[28:29], v[26:27], 2, s[12:13]
	global_load_dwordx4 v[18:21], v[28:29], off
	global_load_dwordx4 v[22:25], v[28:29], off offset:16
	global_load_dwordx4 v[230:233], v[28:29], off offset:512
	global_load_dwordx4 v[234:237], v[28:29], off offset:528
	v_lshl_add_u64 v[26:27], v[26:27], 1, s[16:17]
	s_waitcnt vmcnt(3)
	v_pk_add_f32 v[14:15], v[14:15], v[20:21]
	v_pk_add_f32 v[12:13], v[12:13], v[18:19]
	s_waitcnt vmcnt(2)
	v_pk_add_f32 v[10:11], v[10:11], v[24:25]
	v_pk_add_f32 v[8:9], v[8:9], v[22:23]
	v_cvt_pk_bf16_f32 v18, v12, v13
	v_cvt_pk_bf16_f32 v19, v14, v15
	v_cvt_pk_bf16_f32 v20, v8, v9
	v_cvt_pk_bf16_f32 v21, v10, v11
	global_store_dwordx4 v[28:29], v[12:15], off
	global_store_dwordx4 v[28:29], v[8:11], off offset:16
	global_store_dwordx4 v[26:27], v[18:21], off
	v_mul_f32_e32 v13, v13, v13
	v_fmac_f32_e32 v13, v12, v12
	v_fmac_f32_e32 v13, v14, v14
	v_fmac_f32_e32 v13, v15, v15
	v_fmac_f32_e32 v13, v8, v8
	v_fmac_f32_e32 v13, v9, v9
	v_fmac_f32_e32 v13, v10, v10
	v_fmac_f32_e32 v13, v11, v11
	s_waitcnt vmcnt(4)
	v_pk_add_f32 v[6:7], v[6:7], v[232:233]
	v_pk_add_f32 v[4:5], v[4:5], v[230:231]
	s_waitcnt vmcnt(3)
	v_pk_add_f32 v[2:3], v[2:3], v[236:237]
	v_pk_add_f32 v[0:1], v[0:1], v[234:235]
	global_store_dwordx4 v[28:29], v[4:7], off offset:512
	global_store_dwordx4 v[28:29], v[0:3], off offset:528
	v_cvt_pk_bf16_f32 v8, v4, v5
	v_mul_f32_e32 v5, v5, v5
	v_fmac_f32_e32 v5, v4, v4
	v_fmac_f32_e32 v5, v6, v6
	v_fmac_f32_e32 v5, v7, v7
	v_fmac_f32_e32 v5, v0, v0
	v_fmac_f32_e32 v5, v1, v1
	v_fmac_f32_e32 v5, v2, v2
	v_fmac_f32_e32 v5, v3, v3
	v_add_f32_e32 v4, v13, v5
	ds_swizzle_b32 v5, v4 offset:swizzle(SWAP,16)
	v_cvt_pk_bf16_f32 v10, v0, v1
	v_cvt_pk_bf16_f32 v9, v6, v7
	v_cvt_pk_bf16_f32 v11, v2, v3
	global_store_dwordx4 v[26:27], v[8:11], off offset:256
	s_waitcnt lgkmcnt(0)
	v_add_f32_e32 v0, v4, v5
	v_mov_b32_e32 v1, v0
	s_nop 1
	v_permlane32_swap_b32_e32 v0, v1
	s_and_saveexec_b64 s[38:39], s[8:9]
	s_cbranch_execz .LBB0_597
	v_add_f32_e32 v2, v0, v1
	v_lshlrev_b64 v[0:1], 7, v[16:17]
	v_lshl_add_u64 v[0:1], s[20:21], 0, v[0:1]
	v_lshl_add_u64 v[0:1], s[36:37], 2, v[0:1]
	s_lshl_b32 s22, s53, 2
	v_lshl_add_u64 v[0:1], v[0:1], 0, s[22:23]
	global_store_dword v[0:1], v2, off
	s_branch .LBB0_597

; __device__ __forceinline__ float swz16(float v) { return __builtin_bit_cast(float, __builtin_amdgcn_ds_swizzle(__builtin_bit_cast(int, v), 0x401F)); }
;     __device__ __forceinline__ void operator()(const f32x4 (&acc)[2][2][4][2], const Unit& u, int wr, int wc, int fr, int fq) const {
;     ...
;         for (int ai = 0; ai < 2; ++ai)
; #pragma unroll
;             for (int m = 0; m < 4; ++m) {
;                 const int row = row0 + ai * 128 + m * 16; float sq = 0.f;
; #pragma unroll
;                 for (int bj = 0; bj < 2; ++bj) {
;                     const size_t off = (size_t)row * DM + col0 + bj * 128;
;                     const f32x4 r0 = *(const f32x4*)(res + off), r1 = *(const f32x4*)(res + off + 4);
;                     const f32x4 v0 = acc[ai][bj][m][0] + r0, v1 = acc[ai][bj][m][1] + r1;
;                     *(f32x4*)(out + off) = v0; *(f32x4*)(out + off + 4) = v1;
;                     u32x4 o; o.x = pack2(v0[0], v0[1]); o.y = pack2(v0[2], v0[3]); o.z = pack2(v1[0], v1[1]); o.w = pack2(v1[2], v1[3]);
;                     *(u32x4*)(hb + off) = o;
;                     sq += v0[0] * v0[0] + v0[1] * v0[1] + v0[2] * v0[2] + v0[3] * v0[3] + v1[0] * v1[0] + v1[1] * v1[1] + v1[2] * v1[2] + v1[3] * v1[3];
;                 }
;                 sq += swz16(sq); sq = sum32(sq);
;                 if (fq == 0) ss_out[(size_t)row * 32 + u.pn * 4 + wc] = sq;
;             }
.LBB0_1213:
	s_or_b64 exec, exec, s[36:37]
	v_or_b32_e32 v112, 16, v146
	v_ashrrev_i32_e32 v113, 31, v112
	v_lshlrev_b64 v[114:115], 11, v[112:113]
	v_lshl_add_u64 v[122:123], v[114:115], 0, v[144:145]
	v_lshl_add_u64 v[124:125], v[122:123], 2, s[16:17]
	global_load_dwordx4 v[114:117], v[124:125], off
	global_load_dwordx4 v[118:121], v[124:125], off offset:16
	global_load_dwordx4 v[230:233], v[124:125], off offset:512
	global_load_dwordx4 v[234:237], v[124:125], off offset:528
	v_lshl_add_u64 v[122:123], v[122:123], 1, s[14:15]
	s_waitcnt vmcnt(3)
	v_pk_add_f32 v[110:111], v[110:111], v[116:117]
	v_pk_add_f32 v[108:109], v[108:109], v[114:115]
	s_waitcnt vmcnt(2)
	v_pk_add_f32 v[106:107], v[106:107], v[120:121]
	v_pk_add_f32 v[104:105], v[104:105], v[118:119]
	v_cvt_pk_bf16_f32 v114, v108, v109
	v_cvt_pk_bf16_f32 v115, v110, v111
	v_cvt_pk_bf16_f32 v116, v104, v105
	v_cvt_pk_bf16_f32 v117, v106, v107
	global_store_dwordx4 v[124:125], v[108:111], off
	global_store_dwordx4 v[124:125], v[104:107], off offset:16
	global_store_dwordx4 v[122:123], v[114:117], off
	v_mul_f32_e32 v109, v109, v109
	v_fmac_f32_e32 v109, v108, v108
	v_fmac_f32_e32 v109, v110, v110
	v_fmac_f32_e32 v109, v111, v111
	v_fmac_f32_e32 v109, v104, v104
	v_fmac_f32_e32 v109, v105, v105
	v_fmac_f32_e32 v109, v106, v106
	v_fmac_f32_e32 v109, v107, v107
	s_waitcnt vmcnt(4)
	v_pk_add_f32 v[102:103], v[102:103], v[232:233]
	v_pk_add_f32 v[100:101], v[100:101], v[230:231]
	s_waitcnt vmcnt(3)
	v_pk_add_f32 v[98:99], v[98:99], v[236:237]
	v_pk_add_f32 v[96:97], v[96:97], v[234:235]
	global_store_dwordx4 v[124:125], v[100:103], off offset:512
	global_store_dwordx4 v[124:125], v[96:99], off offset:528
	v_cvt_pk_bf16_f32 v104, v100, v101
	v_mul_f32_e32 v101, v101, v101
	v_fmac_f32_e32 v101, v100, v100
	v_fmac_f32_e32 v101, v102, v102
	v_fmac_f32_e32 v101, v103, v103
	v_fmac_f32_e32 v101, v96, v96
	v_fmac_f32_e32 v101, v97, v97
	v_fmac_f32_e32 v101, v98, v98
	v_fmac_f32_e32 v101, v99, v99
	v_add_f32_e32 v100, v109, v101
	ds_swizzle_b32 v101, v100 offset:swizzle(SWAP,16)
	v_cvt_pk_bf16_f32 v106, v96, v97
	v_cvt_pk_bf16_f32 v105, v102, v103
	v_cvt_pk_bf16_f32 v107, v98, v99
	global_store_dwordx4 v[122:123], v[104:107], off offset:256
	s_waitcnt lgkmcnt(0)
	v_add_f32_e32 v96, v100, v101
	v_mov_b32_e32 v97, v96
	s_nop 1
	v_permlane32_swap_b32_e32 v96, v97
	s_and_saveexec_b64 s[36:37], s[6:7]
	s_cbranch_execz .LBB0_1215
	v_add_f32_e32 v98, v96, v97
	v_lshlrev_b64 v[96:97], 7, v[112:113]
	v_lshl_add_u64 v[96:97], s[10:11], 0, v[96:97]
	v_lshl_add_u64 v[96:97], s[34:35], 2, v[96:97]
	s_lshl_b32 s20, s47, 2
	v_lshl_add_u64 v[96:97], v[96:97], 0, s[20:21]
	global_store_dword v[96:97], v98, off
.LBB0_1215:
	s_or_b64 exec, exec, s[36:37]
	v_or_b32_e32 v96, 32, v146
	v_ashrrev_i32_e32 v97, 31, v96
	v_lshlrev_b64 v[98:99], 11, v[96:97]
	v_lshl_add_u64 v[106:107], v[98:99], 0, v[144:145]
	v_lshl_add_u64 v[108:109], v[106:107], 2, s[16:17]
	global_load_dwordx4 v[98:101], v[108:109], off
	global_load_dwordx4 v[102:105], v[108:109], off offset:16
	global_load_dwordx4 v[230:233], v[108:109], off offset:512
	global_load_dwordx4 v[234:237], v[108:109], off offset:528
	v_lshl_add_u64 v[106:107], v[106:107], 1, s[14:15]
	s_waitcnt vmcnt(3)
	v_pk_add_f32 v[94:95], v[94:95], v[100:101]
	v_pk_add_f32 v[92:93], v[92:93], v[98:99]
	s_waitcnt vmcnt(2)
	v_pk_add_f32 v[90:91], v[90:91], v[104:105]
	v_pk_add_f32 v[88:89], v[88:89], v[102:103]
	v_cvt_pk_bf16_f32 v98, v92, v93
	v_cvt_pk_bf16_f32 v99, v94, v95
	v_cvt_pk_bf16_f32 v100, v88, v89
	v_cvt_pk_bf16_f32 v101, v90, v91
	global_store_dwordx4 v[108:109], v[92:95], off
	global_store_dwordx4 v[108:109], v[88:91], off offset:16
	global_store_dwordx4 v[106:107], v[98:101], off
	v_mul_f32_e32 v93, v93, v93
	v_fmac_f32_e32 v93, v92, v92
	v_fmac_f32_e32 v93, v94, v94
	v_fmac_f32_e32 v93, v95, v95
	v_fmac_f32_e32 v93, v88, v88
	v_fmac_f32_e32 v93, v89, v89
	v_fmac_f32_e32 v93, v90, v90
	v_fmac_f32_e32 v93, v91, v91
	s_waitcnt vmcnt(4)
	v_pk_add_f32 v[86:87], v[86:87], v[232:233]
	v_pk_add_f32 v[84:85], v[84:85], v[230:231]
	s_waitcnt vmcnt(3)
	v_pk_add_f32 v[82:83], v[82:83], v[236:237]
	v_pk_add_f32 v[80:81], v[80:81], v[234:235]
	global_store_dwordx4 v[108:109], v[84:87], off offset:512
	global_store_dwordx4 v[108:109], v[80:83], off offset:528
	v_cvt_pk_bf16_f32 v88, v84, v85
	v_mul_f32_e32 v85, v85, v85
	v_fmac_f32_e32 v85, v84, v84
	v_fmac_f32_e32 v85, v86, v86
	v_fmac_f32_e32 v85, v87, v87
	v_fmac_f32_e32 v85, v80, v80
	v_fmac_f32_e32 v85, v81, v81
	v_fmac_f32_e32 v85, v82, v82
	v_fmac_f32_e32 v85, v83, v83
	v_add_f32_e32 v84, v93, v85
	ds_swizzle_b32 v85, v84 offset:swizzle(SWAP,16)
	v_cvt_pk_bf16_f32 v90, v80, v81
	v_cvt_pk_bf16_f32 v89, v86, v87
	v_cvt_pk_bf16_f32 v91, v82, v83
	global_store_dwordx4 v[106:107], v[88:91], off offset:256
	s_waitcnt lgkmcnt(0)
	v_add_f32_e32 v80, v84, v85
	v_mov_b32_e32 v81, v80
	s_nop 1
	v_permlane32_swap_b32_e32 v80, v81
	s_and_saveexec_b64 s[36:37], s[6:7]
	s_cbranch_execz .LBB0_1217
	v_add_f32_e32 v82, v80, v81
	v_lshlrev_b64 v[80:81], 7, v[96:97]
	v_lshl_add_u64 v[80:81], s[10:11], 0, v[80:81]
	v_lshl_add_u64 v[80:81], s[34:35], 2, v[80:81]
	s_lshl_b32 s20, s47, 2
	v_lshl_add_u64 v[80:81], v[80:81], 0, s[20:21]
	global_store_dword v[80:81], v82, off
; __device__ __forceinline__ float swz16(float v) { return __builtin_bit_cast(float, __builtin_amdgcn_ds_swizzle(__builtin_bit_cast(int, v), 0x401F)); }
;     __device__ __forceinline__ void operator()(const f32x4 (&acc)[2][2][4][2], const Unit& u, int wr, int wc, int fr, int fq) const {
;     ...
;         for (int ai = 0; ai < 2; ++ai)
; #pragma unroll
;             for (int m = 0; m < 4; ++m) {
;                 const int row = row0 + ai * 128 + m * 16; float sq = 0.f;
; #pragma unroll
;                 for (int bj = 0; bj < 2; ++bj) {
;                     const size_t off = (size_t)row * DM + col0 + bj * 128;
;                     const f32x4 r0 = *(const f32x4*)(res + off), r1 = *(const f32x4*)(res + off + 4);
;                     const f32x4 v0 = acc[ai][bj][m][0] + r0, v1 = acc[ai][bj][m][1] + r1;
;                     *(f32x4*)(out + off) = v0; *(f32x4*)(out + off + 4) = v1;
;                     u32x4 o; o.x = pack2(v0[0], v0[1]); o.y = pack2(v0[2], v0[3]); o.z = pack2(v1[0], v1[1]); o.w = pack2(v1[2], v1[3]);
;                     *(u32x4*)(hb + off) = o;
;                     sq += v0[0] * v0[0] + v0[1] * v0[1] + v0[2] * v0[2] + v0[3] * v0[3] + v1[0] * v1[0] + v1[1] * v1[1] + v1[2] * v1[2] + v1[3] * v1[3];
;                 }
;                 sq += swz16(sq); sq = sum32(sq);
;                 if (fq == 0) ss_out[(size_t)row * 32 + u.pn * 4 + wc] = sq;
;             }
.LBB0_1217:
	s_or_b64 exec, exec, s[36:37]
	v_or_b32_e32 v80, 48, v146
	v_ashrrev_i32_e32 v81, 31, v80
	v_lshlrev_b64 v[82:83], 11, v[80:81]
	v_lshl_add_u64 v[90:91], v[82:83], 0, v[144:145]
	v_lshl_add_u64 v[92:93], v[90:91], 2, s[16:17]
	global_load_dwordx4 v[82:85], v[92:93], off
	global_load_dwordx4 v[86:89], v[92:93], off offset:16
	global_load_dwordx4 v[230:233], v[92:93], off offset:512
	global_load_dwordx4 v[234:237], v[92:93], off offset:528
	v_lshl_add_u64 v[90:91], v[90:91], 1, s[14:15]
	s_waitcnt vmcnt(3)
	v_pk_add_f32 v[78:79], v[78:79], v[84:85]
	v_pk_add_f32 v[76:77], v[76:77], v[82:83]
	s_waitcnt vmcnt(2)
	v_pk_add_f32 v[74:75], v[74:75], v[88:89]
	v_pk_add_f32 v[72:73], v[72:73], v[86:87]
	v_cvt_pk_bf16_f32 v82, v76, v77
	v_cvt_pk_bf16_f32 v83, v78, v79
	v_cvt_pk_bf16_f32 v84, v72, v73
	v_cvt_pk_bf16_f32 v85, v74, v75
	global_store_dwordx4 v[92:93], v[76:79], off
	global_store_dwordx4 v[92:93], v[72:75], off offset:16
	global_store_dwordx4 v[90:91], v[82:85], off
	v_mul_f32_e32 v77, v77, v77
	v_fmac_f32_e32 v77, v76, v76
	v_fmac_f32_e32 v77, v78, v78
	v_fmac_f32_e32 v77, v79, v79
	v_fmac_f32_e32 v77, v72, v72
	v_fmac_f32_e32 v77, v73, v73
	v_fmac_f32_e32 v77, v74, v74
	v_fmac_f32_e32 v77, v75, v75
	s_waitcnt vmcnt(4)
	v_pk_add_f32 v[70:71], v[70:71], v[232:233]
	v_pk_add_f32 v[68:69], v[68:69], v[230:231]
	s_waitcnt vmcnt(3)
	v_pk_add_f32 v[66:67], v[66:67], v[236:237]
	v_pk_add_f32 v[64:65], v[64:65], v[234:235]
	global_store_dwordx4 v[92:93], v[68:71], off offset:512
	global_store_dwordx4 v[92:93], v[64:67], off offset:528
	v_cvt_pk_bf16_f32 v72, v68, v69
	v_mul_f32_e32 v69, v69, v69
	v_fmac_f32_e32 v69, v68, v68
	v_fmac_f32_e32 v69, v70, v70
	v_fmac_f32_e32 v69, v71, v71
	v_fmac_f32_e32 v69, v64, v64
	v_fmac_f32_e32 v69, v65, v65
	v_fmac_f32_e32 v69, v66, v66
	v_fmac_f32_e32 v69, v67, v67
	v_add_f32_e32 v68, v77, v69
	ds_swizzle_b32 v69, v68 offset:swizzle(SWAP,16)
	v_cvt_pk_bf16_f32 v74, v64, v65
	v_cvt_pk_bf16_f32 v73, v70, v71
	v_cvt_pk_bf16_f32 v75, v66, v67
	global_store_dwordx4 v[90:91], v[72:75], off offset:256
	s_waitcnt lgkmcnt(0)
	v_add_f32_e32 v64, v68, v69
	v_mov_b32_e32 v65, v64
	s_nop 1
	v_permlane32_swap_b32_e32 v64, v65
	s_and_saveexec_b64 s[36:37], s[6:7]
	s_cbranch_execz .LBB0_1219
	v_add_f32_e32 v66, v64, v65
	v_lshlrev_b64 v[64:65], 7, v[80:81]
	v_lshl_add_u64 v[64:65], s[10:11], 0, v[64:65]
	v_lshl_add_u64 v[64:65], s[34:35], 2, v[64:65]
	s_lshl_b32 s20, s47, 2
	v_lshl_add_u64 v[64:65], v[64:65], 0, s[20:21]
	global_store_dword v[64:65], v66, off
.LBB0_1219:
	s_or_b64 exec, exec, s[36:37]
	v_add_u32_e32 v64, 0x80, v146
	v_ashrrev_i32_e32 v65, 31, v64
	v_lshlrev_b64 v[66:67], 11, v[64:65]
	v_lshl_add_u64 v[74:75], v[66:67], 0, v[144:145]
	v_lshl_add_u64 v[76:77], v[74:75], 2, s[16:17]
	global_load_dwordx4 v[66:69], v[76:77], off
	global_load_dwordx4 v[70:73], v[76:77], off offset:16
	global_load_dwordx4 v[230:233], v[76:77], off offset:512
	global_load_dwordx4 v[234:237], v[76:77], off offset:528
	v_lshl_add_u64 v[74:75], v[74:75], 1, s[14:15]
	s_waitcnt vmcnt(3)
	v_pk_add_f32 v[62:63], v[62:63], v[68:69]
	v_pk_add_f32 v[60:61], v[60:61], v[66:67]
	s_waitcnt vmcnt(2)
	v_pk_add_f32 v[58:59], v[58:59], v[72:73]
	v_pk_add_f32 v[56:57], v[56:57], v[70:71]
	v_cvt_pk_bf16_f32 v66, v60, v61
	v_cvt_pk_bf16_f32 v67, v62, v63
	v_cvt_pk_bf16_f32 v68, v56, v57
	v_cvt_pk_bf16_f32 v69, v58, v59
	global_store_dwordx4 v[76:77], v[60:63], off
	global_store_dwordx4 v[76:77], v[56:59], off offset:16
	global_store_dwordx4 v[74:75], v[66:69], off
	v_mul_f32_e32 v61, v61, v61
	v_fmac_f32_e32 v61, v60, v60
	v_fmac_f32_e32 v61, v62, v62
	v_fmac_f32_e32 v61, v63, v63
	v_fmac_f32_e32 v61, v56, v56
	v_fmac_f32_e32 v61, v57, v57
	v_fmac_f32_e32 v61, v58, v58
	v_fmac_f32_e32 v61, v59, v59
	s_waitcnt vmcnt(4)
	v_pk_add_f32 v[54:55], v[54:55], v[232:233]
	v_pk_add_f32 v[52:53], v[52:53], v[230:231]
	s_waitcnt vmcnt(3)
	v_pk_add_f32 v[50:51], v[50:51], v[236:237]
	v_pk_add_f32 v[48:49], v[48:49], v[234:235]
	global_store_dwordx4 v[76:77], v[52:55], off offset:512
	global_store_dwordx4 v[76:77], v[48:51], off offset:528
	v_cvt_pk_bf16_f32 v56, v52, v53
	v_mul_f32_e32 v53, v53, v53
	v_fmac_f32_e32 v53, v52, v52
	v_fmac_f32_e32 v53, v54, v54
	v_fmac_f32_e32 v53, v55, v55
	v_fmac_f32_e32 v53, v48, v48
	v_fmac_f32_e32 v53, v49, v49
	v_fmac_f32_e32 v53, v50, v50
	v_fmac_f32_e32 v53, v51, v51
	v_add_f32_e32 v52, v61, v53
	ds_swizzle_b32 v53, v52 offset:swizzle(SWAP,16)
	v_cvt_pk_bf16_f32 v58, v48, v49
	v_cvt_pk_bf16_f32 v57, v54, v55
	v_cvt_pk_bf16_f32 v59, v50, v51
	global_store_dwordx4 v[74:75], v[56:59], off offset:256
	s_waitcnt lgkmcnt(0)
	v_add_f32_e32 v48, v52, v53
	v_mov_b32_e32 v49, v48
	s_nop 1
	v_permlane32_swap_b32_e32 v48, v49
	s_and_saveexec_b64 s[36:37], s[6:7]
	s_cbranch_execz .LBB0_1221
	v_add_f32_e32 v50, v48, v49
	v_lshlrev_b64 v[48:49], 7, v[64:65]
	v_lshl_add_u64 v[48:49], s[10:11], 0, v[48:49]
	v_lshl_add_u64 v[48:49], s[34:35], 2, v[48:49]
	s_lshl_b32 s20, s47, 2
	v_lshl_add_u64 v[48:49], v[48:49], 0, s[20:21]
	global_store_dword v[48:49], v50, off
; __device__ __forceinline__ float swz16(float v) { return __builtin_bit_cast(float, __builtin_amdgcn_ds_swizzle(__builtin_bit_cast(int, v), 0x401F)); }
;     __device__ __forceinline__ void operator()(const f32x4 (&acc)[2][2][4][2], const Unit& u, int wr, int wc, int fr, int fq) const {
;     ...
;         for (int ai = 0; ai < 2; ++ai)
; #pragma unroll
;             for (int m = 0; m < 4; ++m) {
;                 const int row = row0 + ai * 128 + m * 16; float sq = 0.f;
; #pragma unroll
;                 for (int bj = 0; bj < 2; ++bj) {
;                     const size_t off = (size_t)row * DM + col0 + bj * 128;
;                     const f32x4 r0 = *(const f32x4*)(res + off), r1 = *(const f32x4*)(res + off + 4);
;                     const f32x4 v0 = acc[ai][bj][m][0] + r0, v1 = acc[ai][bj][m][1] + r1;
;                     *(f32x4*)(out + off) = v0; *(f32x4*)(out + off + 4) = v1;
;                     u32x4 o; o.x = pack2(v0[0], v0[1]); o.y = pack2(v0[2], v0[3]); o.z = pack2(v1[0], v1[1]); o.w = pack2(v1[2], v1[3]);
;                     *(u32x4*)(hb + off) = o;
;                     sq += v0[0] * v0[0] + v0[1] * v0[1] + v0[2] * v0[2] + v0[3] * v0[3] + v1[0] * v1[0] + v1[1] * v1[1] + v1[2] * v1[2] + v1[3] * v1[3];
;                 }
;                 sq += swz16(sq); sq = sum32(sq);
;                 if (fq == 0) ss_out[(size_t)row * 32 + u.pn * 4 + wc] = sq;
;             }
.LBB0_1221:
	s_or_b64 exec, exec, s[36:37]
	v_add_u32_e32 v48, 0x90, v146
	v_ashrrev_i32_e32 v49, 31, v48
	v_lshlrev_b64 v[50:51], 11, v[48:49]
	v_lshl_add_u64 v[58:59], v[50:51], 0, v[144:145]
	v_lshl_add_u64 v[60:61], v[58:59], 2, s[16:17]
	global_load_dwordx4 v[50:53], v[60:61], off
	global_load_dwordx4 v[54:57], v[60:61], off offset:16
	global_load_dwordx4 v[230:233], v[60:61], off offset:512
	global_load_dwordx4 v[234:237], v[60:61], off offset:528
	v_lshl_add_u64 v[58:59], v[58:59], 1, s[14:15]
	s_waitcnt vmcnt(3)
	v_pk_add_f32 v[46:47], v[46:47], v[52:53]
	v_pk_add_f32 v[44:45], v[44:45], v[50:51]
	s_waitcnt vmcnt(2)
	v_pk_add_f32 v[42:43], v[42:43], v[56:57]
	v_pk_add_f32 v[40:41], v[40:41], v[54:55]
	v_cvt_pk_bf16_f32 v50, v44, v45
	v_cvt_pk_bf16_f32 v51, v46, v47
	v_cvt_pk_bf16_f32 v52, v40, v41
	v_cvt_pk_bf16_f32 v53, v42, v43
	global_store_dwordx4 v[60:61], v[44:47], off
	global_store_dwordx4 v[60:61], v[40:43], off offset:16
	global_store_dwordx4 v[58:59], v[50:53], off
	v_mul_f32_e32 v45, v45, v45
	v_fmac_f32_e32 v45, v44, v44
	v_fmac_f32_e32 v45, v46, v46
	v_fmac_f32_e32 v45, v47, v47
	v_fmac_f32_e32 v45, v40, v40
	v_fmac_f32_e32 v45, v41, v41
	v_fmac_f32_e32 v45, v42, v42
	v_fmac_f32_e32 v45, v43, v43
	s_waitcnt vmcnt(4)
	v_pk_add_f32 v[38:39], v[38:39], v[232:233]
	v_pk_add_f32 v[36:37], v[36:37], v[230:231]
	s_waitcnt vmcnt(3)
	v_pk_add_f32 v[34:35], v[34:35], v[236:237]
	v_pk_add_f32 v[32:33], v[32:33], v[234:235]
	global_store_dwordx4 v[60:61], v[36:39], off offset:512
	global_store_dwordx4 v[60:61], v[32:35], off offset:528
	v_cvt_pk_bf16_f32 v40, v36, v37
	v_mul_f32_e32 v37, v37, v37
	v_fmac_f32_e32 v37, v36, v36
	v_fmac_f32_e32 v37, v38, v38
	v_fmac_f32_e32 v37, v39, v39
	v_fmac_f32_e32 v37, v32, v32
	v_fmac_f32_e32 v37, v33, v33
	v_fmac_f32_e32 v37, v34, v34
	v_fmac_f32_e32 v37, v35, v35
	v_add_f32_e32 v36, v45, v37
	ds_swizzle_b32 v37, v36 offset:swizzle(SWAP,16)
	v_cvt_pk_bf16_f32 v42, v32, v33
	v_cvt_pk_bf16_f32 v41, v38, v39
	v_cvt_pk_bf16_f32 v43, v34, v35
	global_store_dwordx4 v[58:59], v[40:43], off offset:256
	s_waitcnt lgkmcnt(0)
	v_add_f32_e32 v32, v36, v37
	v_mov_b32_e32 v33, v32
	s_nop 1
	v_permlane32_swap_b32_e32 v32, v33
	s_and_saveexec_b64 s[36:37], s[6:7]
	s_cbranch_execz .LBB0_1223
	v_add_f32_e32 v34, v32, v33
	v_lshlrev_b64 v[32:33], 7, v[48:49]
	v_lshl_add_u64 v[32:33], s[10:11], 0, v[32:33]
	v_lshl_add_u64 v[32:33], s[34:35], 2, v[32:33]
	s_lshl_b32 s20, s47, 2
	v_lshl_add_u64 v[32:33], v[32:33], 0, s[20:21]
	global_store_dword v[32:33], v34, off
; __device__ __forceinline__ float swz16(float v) { return __builtin_bit_cast(float, __builtin_amdgcn_ds_swizzle(__builtin_bit_cast(int, v), 0x401F)); }
;     __device__ __forceinline__ void operator()(const f32x4 (&acc)[2][2][4][2], const Unit& u, int wr, int wc, int fr, int fq) const {
;     ...
;         for (int ai = 0; ai < 2; ++ai)
; #pragma unroll
;             for (int m = 0; m < 4; ++m) {
;                 const int row = row0 + ai * 128 + m * 16; float sq = 0.f;
; #pragma unroll
;                 for (int bj = 0; bj < 2; ++bj) {
;                     const size_t off = (size_t)row * DM + col0 + bj * 128;
;                     const f32x4 r0 = *(const f32x4*)(res + off), r1 = *(const f32x4*)(res + off + 4);
;                     const f32x4 v0 = acc[ai][bj][m][0] + r0, v1 = acc[ai][bj][m][1] + r1;
;                     *(f32x4*)(out + off) = v0; *(f32x4*)(out + off + 4) = v1;
;                     u32x4 o; o.x = pack2(v0[0], v0[1]); o.y = pack2(v0[2], v0[3]); o.z = pack2(v1[0], v1[1]); o.w = pack2(v1[2], v1[3]);
;                     *(u32x4*)(hb + off) = o;
;                     sq += v0[0] * v0[0] + v0[1] * v0[1] + v0[2] * v0[2] + v0[3] * v0[3] + v1[0] * v1[0] + v1[1] * v1[1] + v1[2] * v1[2] + v1[3] * v1[3];
;                 }
;                 sq += swz16(sq); sq = sum32(sq);
;                 if (fq == 0) ss_out[(size_t)row * 32 + u.pn * 4 + wc] = sq;
;             }
.LBB0_1223:
	s_or_b64 exec, exec, s[36:37]
	v_add_u32_e32 v32, 0xa0, v146
	v_ashrrev_i32_e32 v33, 31, v32
	v_lshlrev_b64 v[34:35], 11, v[32:33]
	v_lshl_add_u64 v[42:43], v[34:35], 0, v[144:145]
	v_lshl_add_u64 v[44:45], v[42:43], 2, s[16:17]
	global_load_dwordx4 v[34:37], v[44:45], off
	global_load_dwordx4 v[38:41], v[44:45], off offset:16
	global_load_dwordx4 v[230:233], v[44:45], off offset:512
	global_load_dwordx4 v[234:237], v[44:45], off offset:528
	v_lshl_add_u64 v[42:43], v[42:43], 1, s[14:15]
	s_waitcnt vmcnt(3)
	v_pk_add_f32 v[30:31], v[30:31], v[36:37]
	v_pk_add_f32 v[28:29], v[28:29], v[34:35]
	s_waitcnt vmcnt(2)
	v_pk_add_f32 v[26:27], v[26:27], v[40:41]
	v_pk_add_f32 v[24:25], v[24:25], v[38:39]
	v_cvt_pk_bf16_f32 v34, v28, v29
	v_cvt_pk_bf16_f32 v35, v30, v31
	v_cvt_pk_bf16_f32 v36, v24, v25
	v_cvt_pk_bf16_f32 v37, v26, v27
	global_store_dwordx4 v[44:45], v[28:31], off
	global_store_dwordx4 v[44:45], v[24:27], off offset:16
	global_store_dwordx4 v[42:43], v[34:37], off
	v_mul_f32_e32 v29, v29, v29
	v_fmac_f32_e32 v29, v28, v28
	v_fmac_f32_e32 v29, v30, v30
	v_fmac_f32_e32 v29, v31, v31
	v_fmac_f32_e32 v29, v24, v24
	v_fmac_f32_e32 v29, v25, v25
	v_fmac_f32_e32 v29, v26, v26
	v_fmac_f32_e32 v29, v27, v27
	s_waitcnt vmcnt(4)
	v_pk_add_f32 v[22:23], v[22:23], v[232:233]
	v_pk_add_f32 v[20:21], v[20:21], v[230:231]
	s_waitcnt vmcnt(3)
	v_pk_add_f32 v[18:19], v[18:19], v[236:237]
	v_pk_add_f32 v[16:17], v[16:17], v[234:235]
	global_store_dwordx4 v[44:45], v[20:23], off offset:512
	global_store_dwordx4 v[44:45], v[16:19], off offset:528
	v_cvt_pk_bf16_f32 v24, v20, v21
	v_mul_f32_e32 v21, v21, v21
	v_fmac_f32_e32 v21, v20, v20
	v_fmac_f32_e32 v21, v22, v22
	v_fmac_f32_e32 v21, v23, v23
	v_fmac_f32_e32 v21, v16, v16
	v_fmac_f32_e32 v21, v17, v17
	v_fmac_f32_e32 v21, v18, v18
	v_fmac_f32_e32 v21, v19, v19
	v_add_f32_e32 v20, v29, v21
	ds_swizzle_b32 v21, v20 offset:swizzle(SWAP,16)
	v_cvt_pk_bf16_f32 v26, v16, v17
	v_cvt_pk_bf16_f32 v25, v22, v23
	v_cvt_pk_bf16_f32 v27, v18, v19
	global_store_dwordx4 v[42:43], v[24:27], off offset:256
	s_waitcnt lgkmcnt(0)
	v_add_f32_e32 v16, v20, v21
	v_mov_b32_e32 v17, v16
	s_nop 1
	v_permlane32_swap_b32_e32 v16, v17
	s_and_saveexec_b64 s[36:37], s[6:7]
	s_cbranch_execz .LBB0_1225
	v_add_f32_e32 v18, v16, v17
	v_lshlrev_b64 v[16:17], 7, v[32:33]
	v_lshl_add_u64 v[16:17], s[10:11], 0, v[16:17]
	v_lshl_add_u64 v[16:17], s[34:35], 2, v[16:17]
	s_lshl_b32 s20, s47, 2
	v_lshl_add_u64 v[16:17], v[16:17], 0, s[20:21]
	global_store_dword v[16:17], v18, off
.LBB0_1225:
	s_or_b64 exec, exec, s[36:37]
	v_add_u32_e32 v16, 0xb0, v146
	v_ashrrev_i32_e32 v17, 31, v16
	v_lshlrev_b64 v[18:19], 11, v[16:17]
	v_lshl_add_u64 v[26:27], v[18:19], 0, v[144:145]
	v_lshl_add_u64 v[28:29], v[26:27], 2, s[16:17]
	global_load_dwordx4 v[18:21], v[28:29], off
	global_load_dwordx4 v[22:25], v[28:29], off offset:16
	global_load_dwordx4 v[230:233], v[28:29], off offset:512
	global_load_dwordx4 v[234:237], v[28:29], off offset:528
	v_lshl_add_u64 v[26:27], v[26:27], 1, s[14:15]
	s_waitcnt vmcnt(3)
	v_pk_add_f32 v[14:15], v[14:15], v[20:21]
	v_pk_add_f32 v[12:13], v[12:13], v[18:19]
	s_waitcnt vmcnt(2)
	v_pk_add_f32 v[10:11], v[10:11], v[24:25]
	v_pk_add_f32 v[8:9], v[8:9], v[22:23]
	v_cvt_pk_bf16_f32 v18, v12, v13
	v_cvt_pk_bf16_f32 v19, v14, v15
	v_cvt_pk_bf16_f32 v20, v8, v9
	v_cvt_pk_bf16_f32 v21, v10, v11
	global_store_dwordx4 v[28:29], v[12:15], off
	global_store_dwordx4 v[28:29], v[8:11], off offset:16
	global_store_dwordx4 v[26:27], v[18:21], off
	v_mul_f32_e32 v13, v13, v13
	v_fmac_f32_e32 v13, v12, v12
	v_fmac_f32_e32 v13, v14, v14
	v_fmac_f32_e32 v13, v15, v15
	v_fmac_f32_e32 v13, v8, v8
	v_fmac_f32_e32 v13, v9, v9
	v_fmac_f32_e32 v13, v10, v10
	v_fmac_f32_e32 v13, v11, v11
	s_waitcnt vmcnt(4)
	v_pk_add_f32 v[6:7], v[6:7], v[232:233]
	v_pk_add_f32 v[4:5], v[4:5], v[230:231]
	s_waitcnt vmcnt(3)
	v_pk_add_f32 v[2:3], v[2:3], v[236:237]
	v_pk_add_f32 v[0:1], v[0:1], v[234:235]
	global_store_dwordx4 v[28:29], v[4:7], off offset:512
	global_store_dwordx4 v[28:29], v[0:3], off offset:528
	v_cvt_pk_bf16_f32 v8, v4, v5
	v_mul_f32_e32 v5, v5, v5
	v_fmac_f32_e32 v5, v4, v4
	v_fmac_f32_e32 v5, v6, v6
	v_fmac_f32_e32 v5, v7, v7
	v_fmac_f32_e32 v5, v0, v0
	v_fmac_f32_e32 v5, v1, v1
	v_fmac_f32_e32 v5, v2, v2
	v_fmac_f32_e32 v5, v3, v3
	v_add_f32_e32 v4, v13, v5
	ds_swizzle_b32 v5, v4 offset:swizzle(SWAP,16)
	v_cvt_pk_bf16_f32 v10, v0, v1
	v_cvt_pk_bf16_f32 v9, v6, v7
	v_cvt_pk_bf16_f32 v11, v2, v3
	global_store_dwordx4 v[26:27], v[8:11], off offset:256
	s_waitcnt lgkmcnt(0)
	v_add_f32_e32 v0, v4, v5
	v_mov_b32_e32 v1, v0
	s_nop 1
	v_permlane32_swap_b32_e32 v0, v1
	s_and_saveexec_b64 s[36:37], s[6:7]
	s_cbranch_execz .LBB0_1202
	v_add_f32_e32 v2, v0, v1
	v_lshlrev_b64 v[0:1], 7, v[16:17]
	v_lshl_add_u64 v[0:1], s[10:11], 0, v[0:1]
	v_lshl_add_u64 v[0:1], s[34:35], 2, v[0:1]
	s_lshl_b32 s20, s47, 2
	v_lshl_add_u64 v[0:1], v[0:1], 0, s[20:21]
	global_store_dword v[0:1], v2, off
	s_branch .LBB0_1202

; __device__ __forceinline__ float swz16(float v) { return __builtin_bit_cast(float, __builtin_amdgcn_ds_swizzle(__builtin_bit_cast(int, v), 0x401F)); }
;     __device__ __forceinline__ void operator()(const f32x4 (&acc)[2][2][4][2], const Unit& u, int wr, int wc, int fr, int fq) const {
;     ...
;         for (int ai = 0; ai < 2; ++ai)
; #pragma unroll
;             for (int m = 0; m < 4; ++m) {
;                 const int row = row0 + ai * 128 + m * 16; float sq = 0.f;
; #pragma unroll
;                 for (int bj = 0; bj < 2; ++bj) {
;                     const size_t off = (size_t)row * DM + col0 + bj * 128;
;                     const f32x4 r0 = *(const f32x4*)(res + off), r1 = *(const f32x4*)(res + off + 4);
;                     const f32x4 v0 = acc[ai][bj][m][0] + r0, v1 = acc[ai][bj][m][1] + r1;
;                     *(f32x4*)(out + off) = v0; *(f32x4*)(out + off + 4) = v1;
;                     u32x4 o; o.x = pack2(v0[0], v0[1]); o.y = pack2(v0[2], v0[3]); o.z = pack2(v1[0], v1[1]); o.w = pack2(v1[2], v1[3]);
;                     *(u32x4*)(hb + off) = o;
;                     sq += v0[0] * v0[0] + v0[1] * v0[1] + v0[2] * v0[2] + v0[3] * v0[3] + v1[0] * v1[0] + v1[1] * v1[1] + v1[2] * v1[2] + v1[3] * v1[3];
;                 }
;                 sq += swz16(sq); sq = sum32(sq);
;                 if (fq == 0) ss_out[(size_t)row * 32 + u.pn * 4 + wc] = sq;
;             }
.LBB0_1283:
	s_or_b64 exec, exec, s[36:37]
	v_or_b32_e32 v112, 16, v146
	v_ashrrev_i32_e32 v113, 31, v112
	v_lshlrev_b64 v[114:115], 11, v[112:113]
	v_lshl_add_u64 v[122:123], v[114:115], 0, v[144:145]
	v_lshl_add_u64 v[124:125], v[122:123], 2, s[12:13]
	global_load_dwordx4 v[114:117], v[124:125], off
	global_load_dwordx4 v[118:121], v[124:125], off offset:16
	global_load_dwordx4 v[230:233], v[124:125], off offset:512
	global_load_dwordx4 v[234:237], v[124:125], off offset:528
	v_lshl_add_u64 v[122:123], v[122:123], 1, s[10:11]
	s_waitcnt vmcnt(3)
	v_pk_add_f32 v[110:111], v[110:111], v[116:117]
	v_pk_add_f32 v[108:109], v[108:109], v[114:115]
	s_waitcnt vmcnt(2)
	v_pk_add_f32 v[106:107], v[106:107], v[120:121]
	v_pk_add_f32 v[104:105], v[104:105], v[118:119]
	v_cvt_pk_bf16_f32 v114, v108, v109
	v_cvt_pk_bf16_f32 v115, v110, v111
	v_cvt_pk_bf16_f32 v116, v104, v105
	v_cvt_pk_bf16_f32 v117, v106, v107
	global_store_dwordx4 v[124:125], v[108:111], off
	global_store_dwordx4 v[124:125], v[104:107], off offset:16
	global_store_dwordx4 v[122:123], v[114:117], off
	v_mul_f32_e32 v109, v109, v109
	v_fmac_f32_e32 v109, v108, v108
	v_fmac_f32_e32 v109, v110, v110
	v_fmac_f32_e32 v109, v111, v111
	v_fmac_f32_e32 v109, v104, v104
	v_fmac_f32_e32 v109, v105, v105
	v_fmac_f32_e32 v109, v106, v106
	v_fmac_f32_e32 v109, v107, v107
	s_waitcnt vmcnt(4)
	v_pk_add_f32 v[102:103], v[102:103], v[232:233]
	v_pk_add_f32 v[100:101], v[100:101], v[230:231]
	s_waitcnt vmcnt(3)
	v_pk_add_f32 v[98:99], v[98:99], v[236:237]
	v_pk_add_f32 v[96:97], v[96:97], v[234:235]
	global_store_dwordx4 v[124:125], v[100:103], off offset:512
	global_store_dwordx4 v[124:125], v[96:99], off offset:528
	v_cvt_pk_bf16_f32 v104, v100, v101
	v_mul_f32_e32 v101, v101, v101
	v_fmac_f32_e32 v101, v100, v100
	v_fmac_f32_e32 v101, v102, v102
	v_fmac_f32_e32 v101, v103, v103
	v_fmac_f32_e32 v101, v96, v96
	v_fmac_f32_e32 v101, v97, v97
	v_fmac_f32_e32 v101, v98, v98
	v_fmac_f32_e32 v101, v99, v99
	v_add_f32_e32 v100, v109, v101
	ds_swizzle_b32 v101, v100 offset:swizzle(SWAP,16)
	v_cvt_pk_bf16_f32 v106, v96, v97
	v_cvt_pk_bf16_f32 v105, v102, v103
	v_cvt_pk_bf16_f32 v107, v98, v99
	global_store_dwordx4 v[122:123], v[104:107], off offset:256
	s_waitcnt lgkmcnt(0)
	v_add_f32_e32 v96, v100, v101
	v_mov_b32_e32 v97, v96
	s_nop 1
	v_permlane32_swap_b32_e32 v96, v97
	s_and_saveexec_b64 s[36:37], s[6:7]
	s_cbranch_execz .LBB0_1285
	v_add_f32_e32 v98, v96, v97
	v_lshlrev_b64 v[96:97], 7, v[112:113]
	v_lshl_add_u64 v[96:97], s[18:19], 0, v[96:97]
	v_lshl_add_u64 v[96:97], s[34:35], 2, v[96:97]
	s_lshl_b32 s20, s47, 2
	v_lshl_add_u64 v[96:97], v[96:97], 0, s[20:21]
	global_store_dword v[96:97], v98, off
.LBB0_1285:
	s_or_b64 exec, exec, s[36:37]
	v_or_b32_e32 v96, 32, v146
	v_ashrrev_i32_e32 v97, 31, v96
	v_lshlrev_b64 v[98:99], 11, v[96:97]
	v_lshl_add_u64 v[106:107], v[98:99], 0, v[144:145]
	v_lshl_add_u64 v[108:109], v[106:107], 2, s[12:13]
	global_load_dwordx4 v[98:101], v[108:109], off
	global_load_dwordx4 v[102:105], v[108:109], off offset:16
	global_load_dwordx4 v[230:233], v[108:109], off offset:512
	global_load_dwordx4 v[234:237], v[108:109], off offset:528
	v_lshl_add_u64 v[106:107], v[106:107], 1, s[10:11]
	s_waitcnt vmcnt(3)
	v_pk_add_f32 v[94:95], v[94:95], v[100:101]
	v_pk_add_f32 v[92:93], v[92:93], v[98:99]
	s_waitcnt vmcnt(2)
	v_pk_add_f32 v[90:91], v[90:91], v[104:105]
	v_pk_add_f32 v[88:89], v[88:89], v[102:103]
	v_cvt_pk_bf16_f32 v98, v92, v93
	v_cvt_pk_bf16_f32 v99, v94, v95
	v_cvt_pk_bf16_f32 v100, v88, v89
	v_cvt_pk_bf16_f32 v101, v90, v91
	global_store_dwordx4 v[108:109], v[92:95], off
	global_store_dwordx4 v[108:109], v[88:91], off offset:16
	global_store_dwordx4 v[106:107], v[98:101], off
	v_mul_f32_e32 v93, v93, v93
	v_fmac_f32_e32 v93, v92, v92
	v_fmac_f32_e32 v93, v94, v94
	v_fmac_f32_e32 v93, v95, v95
	v_fmac_f32_e32 v93, v88, v88
	v_fmac_f32_e32 v93, v89, v89
	v_fmac_f32_e32 v93, v90, v90
	v_fmac_f32_e32 v93, v91, v91
	s_waitcnt vmcnt(4)
	v_pk_add_f32 v[86:87], v[86:87], v[232:233]
	v_pk_add_f32 v[84:85], v[84:85], v[230:231]
	s_waitcnt vmcnt(3)
	v_pk_add_f32 v[82:83], v[82:83], v[236:237]
	v_pk_add_f32 v[80:81], v[80:81], v[234:235]
	global_store_dwordx4 v[108:109], v[84:87], off offset:512
	global_store_dwordx4 v[108:109], v[80:83], off offset:528
	v_cvt_pk_bf16_f32 v88, v84, v85
	v_mul_f32_e32 v85, v85, v85
	v_fmac_f32_e32 v85, v84, v84
	v_fmac_f32_e32 v85, v86, v86
	v_fmac_f32_e32 v85, v87, v87
	v_fmac_f32_e32 v85, v80, v80
	v_fmac_f32_e32 v85, v81, v81
	v_fmac_f32_e32 v85, v82, v82
	v_fmac_f32_e32 v85, v83, v83
	v_add_f32_e32 v84, v93, v85
	ds_swizzle_b32 v85, v84 offset:swizzle(SWAP,16)
	v_cvt_pk_bf16_f32 v90, v80, v81
	v_cvt_pk_bf16_f32 v89, v86, v87
	v_cvt_pk_bf16_f32 v91, v82, v83
	global_store_dwordx4 v[106:107], v[88:91], off offset:256
	s_waitcnt lgkmcnt(0)
	v_add_f32_e32 v80, v84, v85
	v_mov_b32_e32 v81, v80
	s_nop 1
	v_permlane32_swap_b32_e32 v80, v81
	s_and_saveexec_b64 s[36:37], s[6:7]
	s_cbranch_execz .LBB0_1287
	v_add_f32_e32 v82, v80, v81
	v_lshlrev_b64 v[80:81], 7, v[96:97]
	v_lshl_add_u64 v[80:81], s[18:19], 0, v[80:81]
	v_lshl_add_u64 v[80:81], s[34:35], 2, v[80:81]
	s_lshl_b32 s20, s47, 2
	v_lshl_add_u64 v[80:81], v[80:81], 0, s[20:21]
	global_store_dword v[80:81], v82, off
; __device__ __forceinline__ float swz16(float v) { return __builtin_bit_cast(float, __builtin_amdgcn_ds_swizzle(__builtin_bit_cast(int, v), 0x401F)); }
;     __device__ __forceinline__ void operator()(const f32x4 (&acc)[2][2][4][2], const Unit& u, int wr, int wc, int fr, int fq) const {
;     ...
;         for (int ai = 0; ai < 2; ++ai)
; #pragma unroll
;             for (int m = 0; m < 4; ++m) {
;                 const int row = row0 + ai * 128 + m * 16; float sq = 0.f;
; #pragma unroll
;                 for (int bj = 0; bj < 2; ++bj) {
;                     const size_t off = (size_t)row * DM + col0 + bj * 128;
;                     const f32x4 r0 = *(const f32x4*)(res + off), r1 = *(const f32x4*)(res + off + 4);
;                     const f32x4 v0 = acc[ai][bj][m][0] + r0, v1 = acc[ai][bj][m][1] + r1;
;                     *(f32x4*)(out + off) = v0; *(f32x4*)(out + off + 4) = v1;
;                     u32x4 o; o.x = pack2(v0[0], v0[1]); o.y = pack2(v0[2], v0[3]); o.z = pack2(v1[0], v1[1]); o.w = pack2(v1[2], v1[3]);
;                     *(u32x4*)(hb + off) = o;
;                     sq += v0[0] * v0[0] + v0[1] * v0[1] + v0[2] * v0[2] + v0[3] * v0[3] + v1[0] * v1[0] + v1[1] * v1[1] + v1[2] * v1[2] + v1[3] * v1[3];
;                 }
;                 sq += swz16(sq); sq = sum32(sq);
;                 if (fq == 0) ss_out[(size_t)row * 32 + u.pn * 4 + wc] = sq;
;             }
.LBB0_1287:
	s_or_b64 exec, exec, s[36:37]
	v_or_b32_e32 v80, 48, v146
	v_ashrrev_i32_e32 v81, 31, v80
	v_lshlrev_b64 v[82:83], 11, v[80:81]
	v_lshl_add_u64 v[90:91], v[82:83], 0, v[144:145]
	v_lshl_add_u64 v[92:93], v[90:91], 2, s[12:13]
	global_load_dwordx4 v[82:85], v[92:93], off
	global_load_dwordx4 v[86:89], v[92:93], off offset:16
	global_load_dwordx4 v[230:233], v[92:93], off offset:512
	global_load_dwordx4 v[234:237], v[92:93], off offset:528
	v_lshl_add_u64 v[90:91], v[90:91], 1, s[10:11]
	s_waitcnt vmcnt(3)
	v_pk_add_f32 v[78:79], v[78:79], v[84:85]
	v_pk_add_f32 v[76:77], v[76:77], v[82:83]
	s_waitcnt vmcnt(2)
	v_pk_add_f32 v[74:75], v[74:75], v[88:89]
	v_pk_add_f32 v[72:73], v[72:73], v[86:87]
	v_cvt_pk_bf16_f32 v82, v76, v77
	v_cvt_pk_bf16_f32 v83, v78, v79
	v_cvt_pk_bf16_f32 v84, v72, v73
	v_cvt_pk_bf16_f32 v85, v74, v75
	global_store_dwordx4 v[92:93], v[76:79], off
	global_store_dwordx4 v[92:93], v[72:75], off offset:16
	global_store_dwordx4 v[90:91], v[82:85], off
	v_mul_f32_e32 v77, v77, v77
	v_fmac_f32_e32 v77, v76, v76
	v_fmac_f32_e32 v77, v78, v78
	v_fmac_f32_e32 v77, v79, v79
	v_fmac_f32_e32 v77, v72, v72
	v_fmac_f32_e32 v77, v73, v73
	v_fmac_f32_e32 v77, v74, v74
	v_fmac_f32_e32 v77, v75, v75
	s_waitcnt vmcnt(4)
	v_pk_add_f32 v[70:71], v[70:71], v[232:233]
	v_pk_add_f32 v[68:69], v[68:69], v[230:231]
	s_waitcnt vmcnt(3)
	v_pk_add_f32 v[66:67], v[66:67], v[236:237]
	v_pk_add_f32 v[64:65], v[64:65], v[234:235]
	global_store_dwordx4 v[92:93], v[68:71], off offset:512
	global_store_dwordx4 v[92:93], v[64:67], off offset:528
	v_cvt_pk_bf16_f32 v72, v68, v69
	v_mul_f32_e32 v69, v69, v69
	v_fmac_f32_e32 v69, v68, v68
	v_fmac_f32_e32 v69, v70, v70
	v_fmac_f32_e32 v69, v71, v71
	v_fmac_f32_e32 v69, v64, v64
	v_fmac_f32_e32 v69, v65, v65
	v_fmac_f32_e32 v69, v66, v66
	v_fmac_f32_e32 v69, v67, v67
	v_add_f32_e32 v68, v77, v69
	ds_swizzle_b32 v69, v68 offset:swizzle(SWAP,16)
	v_cvt_pk_bf16_f32 v74, v64, v65
	v_cvt_pk_bf16_f32 v73, v70, v71
	v_cvt_pk_bf16_f32 v75, v66, v67
	global_store_dwordx4 v[90:91], v[72:75], off offset:256
	s_waitcnt lgkmcnt(0)
	v_add_f32_e32 v64, v68, v69
	v_mov_b32_e32 v65, v64
	s_nop 1
	v_permlane32_swap_b32_e32 v64, v65
	s_and_saveexec_b64 s[36:37], s[6:7]
	s_cbranch_execz .LBB0_1289
	v_add_f32_e32 v66, v64, v65
	v_lshlrev_b64 v[64:65], 7, v[80:81]
	v_lshl_add_u64 v[64:65], s[18:19], 0, v[64:65]
	v_lshl_add_u64 v[64:65], s[34:35], 2, v[64:65]
	s_lshl_b32 s20, s47, 2
	v_lshl_add_u64 v[64:65], v[64:65], 0, s[20:21]
	global_store_dword v[64:65], v66, off
.LBB0_1289:
	s_or_b64 exec, exec, s[36:37]
	v_add_u32_e32 v64, 0x80, v146
	v_ashrrev_i32_e32 v65, 31, v64
	v_lshlrev_b64 v[66:67], 11, v[64:65]
	v_lshl_add_u64 v[74:75], v[66:67], 0, v[144:145]
	v_lshl_add_u64 v[76:77], v[74:75], 2, s[12:13]
	global_load_dwordx4 v[66:69], v[76:77], off
	global_load_dwordx4 v[70:73], v[76:77], off offset:16
	global_load_dwordx4 v[230:233], v[76:77], off offset:512
	global_load_dwordx4 v[234:237], v[76:77], off offset:528
	v_lshl_add_u64 v[74:75], v[74:75], 1, s[10:11]
	s_waitcnt vmcnt(3)
	v_pk_add_f32 v[62:63], v[62:63], v[68:69]
	v_pk_add_f32 v[60:61], v[60:61], v[66:67]
	s_waitcnt vmcnt(2)
	v_pk_add_f32 v[58:59], v[58:59], v[72:73]
	v_pk_add_f32 v[56:57], v[56:57], v[70:71]
	v_cvt_pk_bf16_f32 v66, v60, v61
	v_cvt_pk_bf16_f32 v67, v62, v63
	v_cvt_pk_bf16_f32 v68, v56, v57
	v_cvt_pk_bf16_f32 v69, v58, v59
	global_store_dwordx4 v[76:77], v[60:63], off
	global_store_dwordx4 v[76:77], v[56:59], off offset:16
	global_store_dwordx4 v[74:75], v[66:69], off
	v_mul_f32_e32 v61, v61, v61
	v_fmac_f32_e32 v61, v60, v60
	v_fmac_f32_e32 v61, v62, v62
	v_fmac_f32_e32 v61, v63, v63
	v_fmac_f32_e32 v61, v56, v56
	v_fmac_f32_e32 v61, v57, v57
	v_fmac_f32_e32 v61, v58, v58
	v_fmac_f32_e32 v61, v59, v59
	s_waitcnt vmcnt(4)
	v_pk_add_f32 v[54:55], v[54:55], v[232:233]
	v_pk_add_f32 v[52:53], v[52:53], v[230:231]
	s_waitcnt vmcnt(3)
	v_pk_add_f32 v[50:51], v[50:51], v[236:237]
	v_pk_add_f32 v[48:49], v[48:49], v[234:235]
	global_store_dwordx4 v[76:77], v[52:55], off offset:512
	global_store_dwordx4 v[76:77], v[48:51], off offset:528
	v_cvt_pk_bf16_f32 v56, v52, v53
	v_mul_f32_e32 v53, v53, v53
	v_fmac_f32_e32 v53, v52, v52
	v_fmac_f32_e32 v53, v54, v54
	v_fmac_f32_e32 v53, v55, v55
	v_fmac_f32_e32 v53, v48, v48
	v_fmac_f32_e32 v53, v49, v49
	v_fmac_f32_e32 v53, v50, v50
	v_fmac_f32_e32 v53, v51, v51
	v_add_f32_e32 v52, v61, v53
	ds_swizzle_b32 v53, v52 offset:swizzle(SWAP,16)
	v_cvt_pk_bf16_f32 v58, v48, v49
	v_cvt_pk_bf16_f32 v57, v54, v55
	v_cvt_pk_bf16_f32 v59, v50, v51
	global_store_dwordx4 v[74:75], v[56:59], off offset:256
	s_waitcnt lgkmcnt(0)
	v_add_f32_e32 v48, v52, v53
	v_mov_b32_e32 v49, v48
	s_nop 1
	v_permlane32_swap_b32_e32 v48, v49
	s_and_saveexec_b64 s[36:37], s[6:7]
	s_cbranch_execz .LBB0_1291
	v_add_f32_e32 v50, v48, v49
	v_lshlrev_b64 v[48:49], 7, v[64:65]
	v_lshl_add_u64 v[48:49], s[18:19], 0, v[48:49]
	v_lshl_add_u64 v[48:49], s[34:35], 2, v[48:49]
	s_lshl_b32 s20, s47, 2
	v_lshl_add_u64 v[48:49], v[48:49], 0, s[20:21]
	global_store_dword v[48:49], v50, off
; __device__ __forceinline__ float swz16(float v) { return __builtin_bit_cast(float, __builtin_amdgcn_ds_swizzle(__builtin_bit_cast(int, v), 0x401F)); }
;     __device__ __forceinline__ void operator()(const f32x4 (&acc)[2][2][4][2], const Unit& u, int wr, int wc, int fr, int fq) const {
;     ...
;         for (int ai = 0; ai < 2; ++ai)
; #pragma unroll
;             for (int m = 0; m < 4; ++m) {
;                 const int row = row0 + ai * 128 + m * 16; float sq = 0.f;
; #pragma unroll
;                 for (int bj = 0; bj < 2; ++bj) {
;                     const size_t off = (size_t)row * DM + col0 + bj * 128;
;                     const f32x4 r0 = *(const f32x4*)(res + off), r1 = *(const f32x4*)(res + off + 4);
;                     const f32x4 v0 = acc[ai][bj][m][0] + r0, v1 = acc[ai][bj][m][1] + r1;
;                     *(f32x4*)(out + off) = v0; *(f32x4*)(out + off + 4) = v1;
;                     u32x4 o; o.x = pack2(v0[0], v0[1]); o.y = pack2(v0[2], v0[3]); o.z = pack2(v1[0], v1[1]); o.w = pack2(v1[2], v1[3]);
;                     *(u32x4*)(hb + off) = o;
;                     sq += v0[0] * v0[0] + v0[1] * v0[1] + v0[2] * v0[2] + v0[3] * v0[3] + v1[0] * v1[0] + v1[1] * v1[1] + v1[2] * v1[2] + v1[3] * v1[3];
;                 }
;                 sq += swz16(sq); sq = sum32(sq);
;                 if (fq == 0) ss_out[(size_t)row * 32 + u.pn * 4 + wc] = sq;
;             }
.LBB0_1291:
	s_or_b64 exec, exec, s[36:37]
	v_add_u32_e32 v48, 0x90, v146
	v_ashrrev_i32_e32 v49, 31, v48
	v_lshlrev_b64 v[50:51], 11, v[48:49]
	v_lshl_add_u64 v[58:59], v[50:51], 0, v[144:145]
	v_lshl_add_u64 v[60:61], v[58:59], 2, s[12:13]
	global_load_dwordx4 v[50:53], v[60:61], off
	global_load_dwordx4 v[54:57], v[60:61], off offset:16
	global_load_dwordx4 v[230:233], v[60:61], off offset:512
	global_load_dwordx4 v[234:237], v[60:61], off offset:528
	v_lshl_add_u64 v[58:59], v[58:59], 1, s[10:11]
	s_waitcnt vmcnt(3)
	v_pk_add_f32 v[46:47], v[46:47], v[52:53]
	v_pk_add_f32 v[44:45], v[44:45], v[50:51]
	s_waitcnt vmcnt(2)
	v_pk_add_f32 v[42:43], v[42:43], v[56:57]
	v_pk_add_f32 v[40:41], v[40:41], v[54:55]
	v_cvt_pk_bf16_f32 v50, v44, v45
	v_cvt_pk_bf16_f32 v51, v46, v47
	v_cvt_pk_bf16_f32 v52, v40, v41
	v_cvt_pk_bf16_f32 v53, v42, v43
	global_store_dwordx4 v[60:61], v[44:47], off
	global_store_dwordx4 v[60:61], v[40:43], off offset:16
	global_store_dwordx4 v[58:59], v[50:53], off
	v_mul_f32_e32 v45, v45, v45
	v_fmac_f32_e32 v45, v44, v44
	v_fmac_f32_e32 v45, v46, v46
	v_fmac_f32_e32 v45, v47, v47
	v_fmac_f32_e32 v45, v40, v40
	v_fmac_f32_e32 v45, v41, v41
	v_fmac_f32_e32 v45, v42, v42
	v_fmac_f32_e32 v45, v43, v43
	s_waitcnt vmcnt(4)
	v_pk_add_f32 v[38:39], v[38:39], v[232:233]
	v_pk_add_f32 v[36:37], v[36:37], v[230:231]
	s_waitcnt vmcnt(3)
	v_pk_add_f32 v[34:35], v[34:35], v[236:237]
	v_pk_add_f32 v[32:33], v[32:33], v[234:235]
	global_store_dwordx4 v[60:61], v[36:39], off offset:512
	global_store_dwordx4 v[60:61], v[32:35], off offset:528
	v_cvt_pk_bf16_f32 v40, v36, v37
	v_mul_f32_e32 v37, v37, v37
	v_fmac_f32_e32 v37, v36, v36
	v_fmac_f32_e32 v37, v38, v38
	v_fmac_f32_e32 v37, v39, v39
	v_fmac_f32_e32 v37, v32, v32
	v_fmac_f32_e32 v37, v33, v33
	v_fmac_f32_e32 v37, v34, v34
	v_fmac_f32_e32 v37, v35, v35
	v_add_f32_e32 v36, v45, v37
	ds_swizzle_b32 v37, v36 offset:swizzle(SWAP,16)
	v_cvt_pk_bf16_f32 v42, v32, v33
	v_cvt_pk_bf16_f32 v41, v38, v39
	v_cvt_pk_bf16_f32 v43, v34, v35
	global_store_dwordx4 v[58:59], v[40:43], off offset:256
	s_waitcnt lgkmcnt(0)
	v_add_f32_e32 v32, v36, v37
	v_mov_b32_e32 v33, v32
	s_nop 1
	v_permlane32_swap_b32_e32 v32, v33
	s_and_saveexec_b64 s[36:37], s[6:7]
	s_cbranch_execz .LBB0_1293
	v_add_f32_e32 v34, v32, v33
	v_lshlrev_b64 v[32:33], 7, v[48:49]
	v_lshl_add_u64 v[32:33], s[18:19], 0, v[32:33]
	v_lshl_add_u64 v[32:33], s[34:35], 2, v[32:33]
	s_lshl_b32 s20, s47, 2
	v_lshl_add_u64 v[32:33], v[32:33], 0, s[20:21]
	global_store_dword v[32:33], v34, off
; __device__ __forceinline__ float swz16(float v) { return __builtin_bit_cast(float, __builtin_amdgcn_ds_swizzle(__builtin_bit_cast(int, v), 0x401F)); }
;     __device__ __forceinline__ void operator()(const f32x4 (&acc)[2][2][4][2], const Unit& u, int wr, int wc, int fr, int fq) const {
;     ...
;         for (int ai = 0; ai < 2; ++ai)
; #pragma unroll
;             for (int m = 0; m < 4; ++m) {
;                 const int row = row0 + ai * 128 + m * 16; float sq = 0.f;
; #pragma unroll
;                 for (int bj = 0; bj < 2; ++bj) {
;                     const size_t off = (size_t)row * DM + col0 + bj * 128;
;                     const f32x4 r0 = *(const f32x4*)(res + off), r1 = *(const f32x4*)(res + off + 4);
;                     const f32x4 v0 = acc[ai][bj][m][0] + r0, v1 = acc[ai][bj][m][1] + r1;
;                     *(f32x4*)(out + off) = v0; *(f32x4*)(out + off + 4) = v1;
;                     u32x4 o; o.x = pack2(v0[0], v0[1]); o.y = pack2(v0[2], v0[3]); o.z = pack2(v1[0], v1[1]); o.w = pack2(v1[2], v1[3]);
;                     *(u32x4*)(hb + off) = o;
;                     sq += v0[0] * v0[0] + v0[1] * v0[1] + v0[2] * v0[2] + v0[3] * v0[3] + v1[0] * v1[0] + v1[1] * v1[1] + v1[2] * v1[2] + v1[3] * v1[3];
;                 }
;                 sq += swz16(sq); sq = sum32(sq);
;                 if (fq == 0) ss_out[(size_t)row * 32 + u.pn * 4 + wc] = sq;
;             }
.LBB0_1293:
	s_or_b64 exec, exec, s[36:37]
	v_add_u32_e32 v32, 0xa0, v146
	v_ashrrev_i32_e32 v33, 31, v32
	v_lshlrev_b64 v[34:35], 11, v[32:33]
	v_lshl_add_u64 v[42:43], v[34:35], 0, v[144:145]
	v_lshl_add_u64 v[44:45], v[42:43], 2, s[12:13]
	global_load_dwordx4 v[34:37], v[44:45], off
	global_load_dwordx4 v[38:41], v[44:45], off offset:16
	global_load_dwordx4 v[230:233], v[44:45], off offset:512
	global_load_dwordx4 v[234:237], v[44:45], off offset:528
	v_lshl_add_u64 v[42:43], v[42:43], 1, s[10:11]
	s_waitcnt vmcnt(3)
	v_pk_add_f32 v[30:31], v[30:31], v[36:37]
	v_pk_add_f32 v[28:29], v[28:29], v[34:35]
	s_waitcnt vmcnt(2)
	v_pk_add_f32 v[26:27], v[26:27], v[40:41]
	v_pk_add_f32 v[24:25], v[24:25], v[38:39]
	v_cvt_pk_bf16_f32 v34, v28, v29
	v_cvt_pk_bf16_f32 v35, v30, v31
	v_cvt_pk_bf16_f32 v36, v24, v25
	v_cvt_pk_bf16_f32 v37, v26, v27
	global_store_dwordx4 v[44:45], v[28:31], off
	global_store_dwordx4 v[44:45], v[24:27], off offset:16
	global_store_dwordx4 v[42:43], v[34:37], off
	v_mul_f32_e32 v29, v29, v29
	v_fmac_f32_e32 v29, v28, v28
	v_fmac_f32_e32 v29, v30, v30
	v_fmac_f32_e32 v29, v31, v31
	v_fmac_f32_e32 v29, v24, v24
	v_fmac_f32_e32 v29, v25, v25
	v_fmac_f32_e32 v29, v26, v26
	v_fmac_f32_e32 v29, v27, v27
	s_waitcnt vmcnt(4)
	v_pk_add_f32 v[22:23], v[22:23], v[232:233]
	v_pk_add_f32 v[20:21], v[20:21], v[230:231]
	s_waitcnt vmcnt(3)
	v_pk_add_f32 v[18:19], v[18:19], v[236:237]
	v_pk_add_f32 v[16:17], v[16:17], v[234:235]
	global_store_dwordx4 v[44:45], v[20:23], off offset:512
	global_store_dwordx4 v[44:45], v[16:19], off offset:528
	v_cvt_pk_bf16_f32 v24, v20, v21
	v_mul_f32_e32 v21, v21, v21
	v_fmac_f32_e32 v21, v20, v20
	v_fmac_f32_e32 v21, v22, v22
	v_fmac_f32_e32 v21, v23, v23
	v_fmac_f32_e32 v21, v16, v16
	v_fmac_f32_e32 v21, v17, v17
	v_fmac_f32_e32 v21, v18, v18
	v_fmac_f32_e32 v21, v19, v19
	v_add_f32_e32 v20, v29, v21
	ds_swizzle_b32 v21, v20 offset:swizzle(SWAP,16)
	v_cvt_pk_bf16_f32 v26, v16, v17
	v_cvt_pk_bf16_f32 v25, v22, v23
	v_cvt_pk_bf16_f32 v27, v18, v19
	global_store_dwordx4 v[42:43], v[24:27], off offset:256
	s_waitcnt lgkmcnt(0)
	v_add_f32_e32 v16, v20, v21
	v_mov_b32_e32 v17, v16
	s_nop 1
	v_permlane32_swap_b32_e32 v16, v17
	s_and_saveexec_b64 s[36:37], s[6:7]
	s_cbranch_execz .LBB0_1295
	v_add_f32_e32 v18, v16, v17
	v_lshlrev_b64 v[16:17], 7, v[32:33]
	v_lshl_add_u64 v[16:17], s[18:19], 0, v[16:17]
	v_lshl_add_u64 v[16:17], s[34:35], 2, v[16:17]
	s_lshl_b32 s20, s47, 2
	v_lshl_add_u64 v[16:17], v[16:17], 0, s[20:21]
	global_store_dword v[16:17], v18, off
.LBB0_1295:
	s_or_b64 exec, exec, s[36:37]
	v_add_u32_e32 v16, 0xb0, v146
	v_ashrrev_i32_e32 v17, 31, v16
	v_lshlrev_b64 v[18:19], 11, v[16:17]
	v_lshl_add_u64 v[26:27], v[18:19], 0, v[144:145]
	v_lshl_add_u64 v[28:29], v[26:27], 2, s[12:13]
	global_load_dwordx4 v[18:21], v[28:29], off
	global_load_dwordx4 v[22:25], v[28:29], off offset:16
	global_load_dwordx4 v[230:233], v[28:29], off offset:512
	global_load_dwordx4 v[234:237], v[28:29], off offset:528
	v_lshl_add_u64 v[26:27], v[26:27], 1, s[10:11]
	s_waitcnt vmcnt(3)
	v_pk_add_f32 v[14:15], v[14:15], v[20:21]
	v_pk_add_f32 v[12:13], v[12:13], v[18:19]
	s_waitcnt vmcnt(2)
	v_pk_add_f32 v[10:11], v[10:11], v[24:25]
	v_pk_add_f32 v[8:9], v[8:9], v[22:23]
	v_cvt_pk_bf16_f32 v18, v12, v13
	v_cvt_pk_bf16_f32 v19, v14, v15
	v_cvt_pk_bf16_f32 v20, v8, v9
	v_cvt_pk_bf16_f32 v21, v10, v11
	global_store_dwordx4 v[28:29], v[12:15], off
	global_store_dwordx4 v[28:29], v[8:11], off offset:16
	global_store_dwordx4 v[26:27], v[18:21], off
	v_mul_f32_e32 v13, v13, v13
	v_fmac_f32_e32 v13, v12, v12
	v_fmac_f32_e32 v13, v14, v14
	v_fmac_f32_e32 v13, v15, v15
	v_fmac_f32_e32 v13, v8, v8
	v_fmac_f32_e32 v13, v9, v9
	v_fmac_f32_e32 v13, v10, v10
	v_fmac_f32_e32 v13, v11, v11
	s_waitcnt vmcnt(4)
	v_pk_add_f32 v[6:7], v[6:7], v[232:233]
	v_pk_add_f32 v[4:5], v[4:5], v[230:231]
	s_waitcnt vmcnt(3)
	v_pk_add_f32 v[2:3], v[2:3], v[236:237]
	v_pk_add_f32 v[0:1], v[0:1], v[234:235]
	global_store_dwordx4 v[28:29], v[4:7], off offset:512
	global_store_dwordx4 v[28:29], v[0:3], off offset:528
	v_cvt_pk_bf16_f32 v8, v4, v5
	v_mul_f32_e32 v5, v5, v5
	v_fmac_f32_e32 v5, v4, v4
	v_fmac_f32_e32 v5, v6, v6
	v_fmac_f32_e32 v5, v7, v7
	v_fmac_f32_e32 v5, v0, v0
	v_fmac_f32_e32 v5, v1, v1
	v_fmac_f32_e32 v5, v2, v2
	v_fmac_f32_e32 v5, v3, v3
	v_add_f32_e32 v4, v13, v5
	ds_swizzle_b32 v5, v4 offset:swizzle(SWAP,16)
	v_cvt_pk_bf16_f32 v10, v0, v1
	v_cvt_pk_bf16_f32 v9, v6, v7
	v_cvt_pk_bf16_f32 v11, v2, v3
	global_store_dwordx4 v[26:27], v[8:11], off offset:256
	s_waitcnt lgkmcnt(0)
	v_add_f32_e32 v0, v4, v5
	v_mov_b32_e32 v1, v0
	s_nop 1
	v_permlane32_swap_b32_e32 v0, v1
	s_and_saveexec_b64 s[36:37], s[6:7]
	s_cbranch_execz .LBB0_1272
	v_add_f32_e32 v2, v0, v1
	v_lshlrev_b64 v[0:1], 7, v[16:17]
	v_lshl_add_u64 v[0:1], s[18:19], 0, v[0:1]
	v_lshl_add_u64 v[0:1], s[34:35], 2, v[0:1]
	s_lshl_b32 s20, s47, 2
	v_lshl_add_u64 v[0:1], v[0:1], 0, s[20:21]
	global_store_dword v[0:1], v2, off
	s_branch .LBB0_1272
